# MLA: j1 exponent offset for the no-rescale path also computed between QK MFMAs
# baseline (speedup 1.0000x reference)
; #define LAS __attribute__((address_space(3)))
; __device__ __forceinline__ float ex2(float x) { return __builtin_amdgcn_exp2f(x); }
; __device__ __forceinline__ f32x4 mfma16(bf16x8 a, bf16x8 b, f32x4 c) { return __builtin_amdgcn_mfma_f32_16x16x32_bf16(a, b, c, 0, 0, 0); }
;   __device__ __forceinline__ bf16_t* W() const { return (bf16_t*)(ws + WS_W); }
; template <int NT, int NKK, int NDT, int MODE, bool MASK> ...
;     ...
;   f32x4 s[NT][4];
;   __builtin_amdgcn_s_setprio(1);
; #pragma unroll
;   for (int t = 0; t < 4; ++t)
; #pragma unroll
;     for (int kk = 0; kk < NKK; ++kk) {
;       const bf16x8 kf = *(LAS const bf16x8*)(Kl + (16 * t + r) * KSTR + (32 * kk + 8 * lg) * 2);
; #pragma unroll
;       for (int j = 0; j < NT; ++j) s[j][t] = mfma16(kf, qf[j][kk], kk == 0 ? (f32x4){0.f, 0.f, 0.f, 0.f} : s[j][t]);
;     }
;   __builtin_amdgcn_s_setprio(0);
;   bf16x8 pf[NT][2];
; #pragma unroll
;   for (int j = 0; j < NT; ++j) {
;     float mx = -INFINITY;
; #pragma unroll
;     for (int t = 0; t < 4; ++t)
; #pragma unroll
;       for (int i = 0; i < 4; ++i) {
;         if (MASK) { const int kp = kpos0 + 16 * t + 4 * lg + i; if (!mask_ok<MODE>(tq[j], kp, W)) s[j][t][i] = -INFINITY; }
;         mx = fmaxf(mx, s[j][t][i]);
;       }
;     mx = max_x16_x32(mx);
;     if (__any(mx > m[j] + 8.0f / c)) {
;       const float mnew = fmaxf(m[j], mx);
;       const float ms2 = (mnew == -INFINITY) ? 0.f : mnew;
;       const float alpha = ex2((m[j] - ms2) * c);
;       m[j] = mnew; l[j] *= alpha;
; #pragma unroll
;       for (int dt = 0; dt < NDT; ++dt) o[j][dt] *= alpha;
;     }
;     const float mc = ((m[j] == -INFINITY) ? 0.f : m[j]) * c;
.LBB0_768:
	s_waitcnt lgkmcnt(0)
	s_barrier
	s_add_i32 s8, s69, 0xffffff41
	s_cmp_gt_i32 s8, s68
	s_cbranch_scc1 .LBB0_797
	s_add_i32 s8, s69, 0xffffff80
	s_cmp_gt_i32 s8, s59
	s_setprio 1
	v_add_u32_e32 v1, s71, v236
	s_waitcnt lgkmcnt(0)
	v_add_u32_e32 v94, v1, v237
	ds_read_b128 v[134:137], v94
	ds_read_b128 v[130:133], v94 offset:64
	ds_read_b128 v[126:129], v94 offset:128
	ds_read_b128 v[122:125], v94 offset:3328
	ds_read_b128 v[118:121], v94 offset:3392
	ds_read_b128 v[114:117], v94 offset:3456
	ds_read_b128 v[106:109], v94 offset:6656
	ds_read_b128 v[98:101], v94 offset:6720
	v_add_u32_e32 v201, v1, v238
	ds_read_b128 v[110:113], v94 offset:6784
	ds_read_b128 v[102:105], v201
	ds_read_b128 v[94:97], v201 offset:64
	s_mov_b64 s[20:21], -1
	v_add_f32_e32 v1, 0x4259535f, v220
	s_cbranch_scc1 .LBB0_788
	s_waitcnt lgkmcnt(10)
	v_mfma_f32_16x16x32_bf16 v[138:141], v[134:137], v[18:21], 0
	ds_read_b128 v[146:149], v201 offset:128
	v_mov_b32_e32 v234, 0x260
	v_mfma_f32_16x16x32_bf16 v[142:145], v[134:137], v[10:13], 0
	s_waitcnt lgkmcnt(10)
	v_mfma_f32_16x16x32_bf16 v[138:141], v[130:133], v[2:5], v[138:141]
	v_mov_b64_e32 v[222:223], v[220:221]
	v_mfma_f32_16x16x32_bf16 v[142:145], v[130:133], v[14:17], v[142:145]
	v_mov_b64_e32 v[224:225], v[218:219]
	s_waitcnt lgkmcnt(9)
	v_mfma_f32_16x16x32_bf16 v[182:185], v[126:129], v[6:9], v[138:141]
	v_mfma_f32_16x16x32_bf16 v[166:169], v[126:129], v[22:25], v[142:145]
	v_mov_b32_e32 v187, v220
	s_waitcnt lgkmcnt(8)
	v_mfma_f32_16x16x32_bf16 v[138:141], v[122:125], v[18:21], 0
	v_add_f32_e32 v158, 0x4259535f, v221
	v_mfma_f32_16x16x32_bf16 v[142:145], v[122:125], v[10:13], 0
	v_mul_f32_e32 v159, 0x3e16c740, v220
	s_waitcnt lgkmcnt(7)
	v_mfma_f32_16x16x32_bf16 v[138:141], v[118:121], v[2:5], v[138:141]
	v_cmp_neq_f32_e64 s[22:23], s81, v220
	v_mfma_f32_16x16x32_bf16 v[142:145], v[118:121], v[14:17], v[142:145]
	s_waitcnt lgkmcnt(6)
	v_mfma_f32_16x16x32_bf16 v[178:181], v[114:117], v[6:9], v[138:141]
	v_mfma_f32_16x16x32_bf16 v[154:157], v[114:117], v[22:25], v[142:145]
	v_cndmask_b32_e64 v159, 0, v159, s[22:23]
	s_waitcnt lgkmcnt(5)
	v_mfma_f32_16x16x32_bf16 v[138:141], v[106:109], v[18:21], 0
	v_mul_f32_e32 v160, 0x3e16c740, v221
	v_mfma_f32_16x16x32_bf16 v[142:145], v[106:109], v[10:13], 0
	v_cmp_neq_f32_e64 s[22:23], s81, v221
	v_max3_f32 v188, v182, s81, v183
	s_waitcnt lgkmcnt(4)
	v_mfma_f32_16x16x32_bf16 v[138:141], v[98:101], v[2:5], v[138:141]
	v_max3_f32 v188, v188, v184, v185
	v_mfma_f32_16x16x32_bf16 v[142:145], v[98:101], v[14:17], v[142:145]
	v_max3_f32 v189, v166, s81, v167
	s_waitcnt lgkmcnt(3)
	v_mfma_f32_16x16x32_bf16 v[174:177], v[110:113], v[6:9], v[138:141]
	v_cndmask_b32_e64 v160, 0, v160, s[22:23]
	v_max3_f32 v189, v189, v168, v169
	v_mfma_f32_16x16x32_bf16 v[150:153], v[110:113], v[22:25], v[142:145]
	s_waitcnt lgkmcnt(2)
	v_mfma_f32_16x16x32_bf16 v[138:141], v[102:105], v[18:21], 0
	v_mfma_f32_16x16x32_bf16 v[142:145], v[102:105], v[10:13], 0
	v_max3_f32 v188, v188, v178, v179
	s_waitcnt lgkmcnt(1)
	v_mfma_f32_16x16x32_bf16 v[138:141], v[94:97], v[2:5], v[138:141]
	v_max3_f32 v188, v188, v180, v181
	v_mfma_f32_16x16x32_bf16 v[142:145], v[94:97], v[14:17], v[142:145]
	v_max3_f32 v189, v189, v154, v155
	s_waitcnt lgkmcnt(0)
	v_mfma_f32_16x16x32_bf16 v[170:173], v[146:149], v[6:9], v[138:141]
	v_max3_f32 v189, v189, v156, v157
	v_mfma_f32_16x16x32_bf16 v[142:145], v[146:149], v[22:25], v[142:145]
	s_setprio 0
	s_nop 3
	v_max3_f32 v138, v188, v174, v175
	v_max3_f32 v138, v138, v176, v177
	v_max3_f32 v138, v138, v170, v171
	v_max3_f32 v138, v138, v172, v173
	v_mov_b32_e32 v139, v138
	s_nop 1
	v_permlane16_swap_b32_e32 v138, v139
	v_max_f32_e32 v138, v138, v139
	v_mov_b32_e32 v139, v138
	s_nop 1
	v_permlane32_swap_b32_e32 v138, v139
	v_max_f32_e32 v186, v138, v139
	v_cmp_gt_f32_e32 vcc, v186, v1
	s_cbranch_vccz .LBB0_772
	v_max_f32_e32 v138, v186, v186
	v_max_f32_e32 v139, v220, v220
	v_max_f32_e32 v222, v139, v138
	v_cmp_neq_f32_e32 vcc, s81, v222
	v_mov_b32_e32 v223, v221
	v_mov_b32_e32 v225, v219
	v_cndmask_b32_e32 v138, 0, v222, vcc
	v_sub_f32_e32 v138, v220, v138
	v_mul_f32_e32 v138, 0x3e16c740, v138
	v_exp_f32_e32 v138, v138
	v_mov_b32_e32 v187, v222
	v_mul_f32_e32 v224, v218, v138
	v_pk_mul_f32 v[92:93], v[92:93], v[138:139] op_sel_hi:[1,0]
	v_pk_mul_f32 v[90:91], v[90:91], v[138:139] op_sel_hi:[1,0]
	v_pk_mul_f32 v[88:89], v[88:89], v[138:139] op_sel_hi:[1,0]
	v_pk_mul_f32 v[86:87], v[86:87], v[138:139] op_sel_hi:[1,0]
	v_pk_mul_f32 v[76:77], v[76:77], v[138:139] op_sel_hi:[1,0]
	v_pk_mul_f32 v[74:75], v[74:75], v[138:139] op_sel_hi:[1,0]
	v_pk_mul_f32 v[68:69], v[68:69], v[138:139] op_sel_hi:[1,0]
	v_pk_mul_f32 v[66:67], v[66:67], v[138:139] op_sel_hi:[1,0]
	v_mul_f32_e32 v159, 0x3e16c740, v187
	v_cmp_neq_f32_e32 vcc, s81, v187
	s_nop 1
	v_cndmask_b32_e32 v159, 0, v159, vcc
; __device__ __forceinline__ float ex2(float x) { return __builtin_amdgcn_exp2f(x); }
;   __device__ __forceinline__ bf16_t* W() const { return (bf16_t*)(ws + WS_W); }
; template <int NT, int NKK, int NDT, int MODE, bool MASK> ...
;     ...
;   for (int j = 0; j < NT; ++j) {
;     float mx = -INFINITY;
; #pragma unroll
;     for (int t = 0; t < 4; ++t)
; #pragma unroll
;       for (int i = 0; i < 4; ++i) {
;         if (MASK) { const int kp = kpos0 + 16 * t + 4 * lg + i; if (!mask_ok<MODE>(tq[j], kp, W)) s[j][t][i] = -INFINITY; }
;         mx = fmaxf(mx, s[j][t][i]);
;       }
;     mx = max_x16_x32(mx);
;     if (__any(mx > m[j] + 8.0f / c)) {
;       const float mnew = fmaxf(m[j], mx);
;       const float ms2 = (mnew == -INFINITY) ? 0.f : mnew;
;       const float alpha = ex2((m[j] - ms2) * c);
;       m[j] = mnew; l[j] *= alpha;
; #pragma unroll
;       for (int dt = 0; dt < NDT; ++dt) o[j][dt] *= alpha;
;     }
;     const float mc = ((m[j] == -INFINITY) ? 0.f : m[j]) * c;
;     float p[4][4], ps = 0.f;
; #pragma unroll
;     for (int t = 0; t < 4; ++t)
; #pragma unroll
;       for (int i = 0; i < 4; ++i) { p[t][i] = ex2(s[j][t][i] * c - mc); ps += p[t][i]; }
;     l[j] += ps;
.LBB0_772:
	v_fma_f32 v182, v182, s88, -v159
	v_exp_f32_e32 v205, v182
	v_fma_f32 v182, v183, s88, -v159
	v_exp_f32_e32 v207, v182
	v_fma_f32 v182, v184, s88, -v159
	v_exp_f32_e32 v246, v182
	v_fma_f32 v182, v185, s88, -v159
	v_exp_f32_e32 v247, v182
	v_fma_f32 v178, v178, s88, -v159
	v_exp_f32_e32 v248, v178
	v_fma_f32 v178, v179, s88, -v159
	v_add_f32_e32 v182, v207, v205
	v_exp_f32_e32 v249, v178
	v_fma_f32 v178, v180, s88, -v159
	v_add_f32_e32 v182, v246, v182
	v_exp_f32_e32 v250, v178
	v_fma_f32 v178, v181, s88, -v159
	v_add_f32_e32 v182, v247, v182
	v_exp_f32_e32 v251, v178
	v_fma_f32 v174, v174, s88, -v159
	v_add_f32_e32 v178, v248, v182
	v_exp_f32_e32 v252, v174
	v_fma_f32 v174, v175, s88, -v159
	v_add_f32_e32 v178, v249, v178
	v_exp_f32_e32 v231, v174
	v_fma_f32 v174, v176, s88, -v159
	v_add_f32_e32 v178, v250, v178
	v_exp_f32_e32 v229, v174
	v_fma_f32 v174, v177, s88, -v159
	v_add_f32_e32 v178, v251, v178
	v_exp_f32_e32 v230, v174
	v_fma_f32 v170, v170, s88, -v159
	v_add_f32_e32 v174, v252, v178
	v_exp_f32_e32 v232, v170
	v_fma_f32 v170, v171, s88, -v159
	v_add_f32_e32 v174, v231, v174
	v_exp_f32_e32 v228, v170
	v_fma_f32 v170, v172, s88, -v159
	v_add_f32_e32 v174, v229, v174
	v_exp_f32_e32 v196, v170
	v_fma_f32 v170, v173, s88, -v159
	v_add_f32_e32 v174, v230, v174
	v_exp_f32_e32 v173, v170
	v_add_f32_e32 v170, v232, v174
	v_add_f32_e32 v170, v228, v170
	v_add_f32_e32 v170, v196, v170
	v_add_f32_e32 v170, v173, v170
	v_add_f32_e32 v224, v224, v170
	v_max3_f32 v170, v189, v150, v151
	v_max3_f32 v170, v170, v152, v153
	v_max3_f32 v170, v170, v142, v143
	v_max3_f32 v170, v170, v144, v145
	v_mov_b32_e32 v171, v170
	s_nop 1
	v_permlane16_swap_b32_e32 v170, v171
	v_max_f32_e32 v170, v170, v171
	v_mov_b32_e32 v171, v170
	s_nop 1
	v_permlane32_swap_b32_e32 v170, v171
	v_max_f32_e32 v170, v170, v171
	v_cmp_gt_f32_e32 vcc, v170, v158
	s_cbranch_vccz .LBB0_786
	v_max_f32_e32 v170, v170, v170
	v_max_f32_e32 v171, v223, v223
	v_max_f32_e32 v197, v171, v170
	v_cmp_neq_f32_e32 vcc, s81, v197
	s_nop 1
	v_cndmask_b32_e32 v170, 0, v197, vcc
	v_sub_f32_e32 v170, v223, v170
	v_mul_f32_e32 v170, 0x3e16c740, v170
	v_exp_f32_e32 v170, v170
	v_mov_b32_e32 v223, v197
	v_mul_f32_e32 v225, v225, v170
	v_pk_mul_f32 v[84:85], v[84:85], v[170:171] op_sel_hi:[1,0]
	v_pk_mul_f32 v[82:83], v[82:83], v[170:171] op_sel_hi:[1,0]
	v_pk_mul_f32 v[80:81], v[80:81], v[170:171] op_sel_hi:[1,0]
	v_pk_mul_f32 v[78:79], v[78:79], v[170:171] op_sel_hi:[1,0]
	v_pk_mul_f32 v[72:73], v[72:73], v[170:171] op_sel_hi:[1,0]
	v_pk_mul_f32 v[70:71], v[70:71], v[170:171] op_sel_hi:[1,0]
	v_pk_mul_f32 v[64:65], v[64:65], v[170:171] op_sel_hi:[1,0]
	v_pk_mul_f32 v[62:63], v[62:63], v[170:171] op_sel_hi:[1,0]
	v_mul_f32_e32 v160, 0x3e16c740, v197
	v_cmp_neq_f32_e32 vcc, s81, v197
	s_nop 1
	v_cndmask_b32_e32 v160, 0, v160, vcc
	s_branch .LBB0_787

; __device__ __forceinline__ float ex2(float x) { return __builtin_amdgcn_exp2f(x); }
; __device__ __forceinline__ f32x4 mfma16(bf16x8 a, bf16x8 b, f32x4 c) { return __builtin_amdgcn_mfma_f32_16x16x32_bf16(a, b, c, 0, 0, 0); }
; __device__ __forceinline__ s16x4 ds_tr(LAS const unsigned char* p) { return __builtin_bit_cast(s16x4, __builtin_amdgcn_ds_read_tr16_b64_v4i16((LAS v4i16_t*)p)); }
; template <int NT, int NKK, int NDT, int MODE, bool MASK> ...
;     ...
;     const float mc = ((m[j] == -INFINITY) ? 0.f : m[j]) * c;
;     float p[4][4], ps = 0.f;
; #pragma unroll
;     for (int t = 0; t < 4; ++t)
; #pragma unroll
;       for (int i = 0; i < 4; ++i) { p[t][i] = ex2(s[j][t][i] * c - mc); ps += p[t][i]; }
;     l[j] += ps;
;     pf[j][0] = pack8(p[0], p[1]); pf[j][1] = pack8(p[2], p[3]);
;   }
;   __builtin_amdgcn_s_setprio(1);
; #pragma unroll
;   for (int st = 0; st < 2; ++st)
; #pragma unroll
;     for (int dt = 0; dt < NDT; ++dt) {
;       const s16x4 v0 = ds_tr(Vl + (32 * st + 4 * lg + vq) * VSTR + (16 * dt + 4 * vp) * 2);
;       const s16x4 v1 = ds_tr(Vl + (32 * st + 16 + 4 * lg + vq) * VSTR + (16 * dt + 4 * vp) * 2);
;       const bf16x8 vf = (bf16x8){v0[0], v0[1], v0[2], v0[3], v1[0], v1[1], v1[2], v1[3]};
; #pragma unroll
;       for (int j = 0; j < NT; ++j) o[j][dt] = mfma16(vf, pf[j][st], o[j][dt]);
;     }
.LBB0_786:
.LBB0_787:
	v_cvt_pk_bf16_f32 v173, v196, v173
	v_cvt_pk_bf16_f32 v172, v232, v228
	v_cvt_pk_bf16_f32 v228, v205, v207
	v_fma_f32 v166, v166, s88, -v160
	v_exp_f32_e32 v166, v166
	v_fma_f32 v167, v167, s88, -v160
	v_exp_f32_e32 v167, v167
	v_fma_f32 v168, v168, s88, -v160
	v_exp_f32_e32 v168, v168
	v_fma_f32 v169, v169, s88, -v160
	v_exp_f32_e32 v169, v169
	v_fma_f32 v154, v154, s88, -v160
	v_exp_f32_e32 v154, v154
	v_fma_f32 v155, v155, s88, -v160
	v_add_f32_e32 v197, v167, v166
	v_exp_f32_e32 v155, v155
	v_fma_f32 v156, v156, s88, -v160
	v_add_f32_e32 v197, v168, v197
	v_exp_f32_e32 v156, v156
	v_fma_f32 v157, v157, s88, -v160
	v_add_f32_e32 v197, v169, v197
	v_exp_f32_e32 v157, v157
	v_fma_f32 v150, v150, s88, -v160
	v_add_f32_e32 v197, v154, v197
	v_exp_f32_e32 v150, v150
	v_fma_f32 v151, v151, s88, -v160
	v_add_f32_e32 v197, v155, v197
	v_exp_f32_e32 v151, v151
	v_fma_f32 v152, v152, s88, -v160
	v_add_f32_e32 v197, v156, v197
	v_exp_f32_e32 v152, v152
	v_fma_f32 v153, v153, s88, -v160
	v_add_f32_e32 v197, v157, v197
	v_exp_f32_e32 v153, v153
	v_fma_f32 v142, v142, s88, -v160
	v_add_f32_e32 v197, v150, v197
	v_exp_f32_e32 v198, v142
	v_fma_f32 v142, v143, s88, -v160
	v_add_f32_e32 v197, v151, v197
	v_exp_f32_e32 v199, v142
	v_fma_f32 v142, v144, s88, -v160
	v_add_f32_e32 v197, v152, v197
	v_exp_f32_e32 v205, v142
	v_fma_f32 v142, v145, s88, -v160
	v_add_f32_e32 v197, v153, v197
	v_exp_f32_e32 v196, v142
	v_add_f32_e32 v142, v198, v197
	v_add_f32_e32 v142, v199, v142
	v_add_f32_e32 v142, v205, v142
	v_add_f32_e32 v142, v196, v142
	v_add_f32_e32 v225, v225, v142
	v_cvt_pk_bf16_f32 v142, v166, v167
	v_cvt_pk_bf16_f32 v143, v168, v169
	v_cvt_pk_bf16_f32 v144, v154, v155
	v_cvt_pk_bf16_f32 v145, v156, v157
	v_cvt_pk_bf16_f32 v170, v252, v231
	v_cvt_pk_bf16_f32 v171, v229, v230
	v_cvt_pk_bf16_f32 v229, v246, v247
	v_cvt_pk_bf16_f32 v230, v248, v249
	v_cvt_pk_bf16_f32 v231, v250, v251
	v_cvt_pk_bf16_f32 v246, v150, v151
	v_cvt_pk_bf16_f32 v247, v152, v153
	v_cvt_pk_bf16_f32 v248, v198, v199
	v_cvt_pk_bf16_f32 v249, v205, v196
	s_setprio 1
	v_add3_u32 v196, s71, v240, v239
	ds_read_b64_tr_b16 v[152:153], v196 offset:15872
	ds_read_b64_tr_b16 v[150:151], v196 offset:13312
	ds_read_b64_tr_b16 v[154:155], v196 offset:13344
	ds_read_b64_tr_b16 v[156:157], v196 offset:15904
	ds_read_b64_tr_b16 v[166:167], v196 offset:13376
	ds_read_b64_tr_b16 v[168:169], v196 offset:15936
	s_mov_b64 s[20:21], 0
	s_waitcnt lgkmcnt(4)
	v_mfma_f32_16x16x32_bf16 v[158:161], v[150:153], v[228:231], v[90:93]
	v_mfma_f32_16x16x32_bf16 v[150:153], v[150:153], v[142:145], v[82:85]
	v_mov_b64_e32 v[218:219], v[224:225]
	s_waitcnt lgkmcnt(0)
	v_mfma_f32_16x16x32_bf16 v[182:185], v[166:169], v[228:231], v[74:77]
	s_nop 2
	ds_read_b64_tr_b16 v[146:147], v196 offset:13408
	ds_read_b64_tr_b16 v[148:149], v196 offset:15968
	v_mfma_f32_16x16x32_bf16 v[162:165], v[154:157], v[228:231], v[86:89]
	v_mov_b64_e32 v[220:221], v[222:223]
	v_mfma_f32_16x16x32_bf16 v[154:157], v[154:157], v[142:145], v[78:81]
	v_mfma_f32_16x16x32_bf16 v[166:169], v[166:169], v[142:145], v[70:73]
	s_waitcnt lgkmcnt(0)
	v_mfma_f32_16x16x32_bf16 v[174:177], v[146:149], v[142:145], v[62:65]
	ds_read_b64_tr_b16 v[142:143], v196 offset:18432
	ds_read_b64_tr_b16 v[144:145], v196 offset:20992
	v_mfma_f32_16x16x32_bf16 v[178:181], v[146:149], v[228:231], v[66:69]
	s_waitcnt lgkmcnt(0)
	v_mfma_f32_16x16x32_bf16 v[90:93], v[142:145], v[170:173], v[158:161]
	v_mfma_f32_16x16x32_bf16 v[82:85], v[142:145], v[246:249], v[150:153]
	s_nop 2
	ds_read_b64_tr_b16 v[150:151], v196 offset:18464
	ds_read_b64_tr_b16 v[152:153], v196 offset:21024
	ds_read_b64_tr_b16 v[158:159], v196 offset:18496
	ds_read_b64_tr_b16 v[160:161], v196 offset:21056
	s_waitcnt lgkmcnt(2)
	v_mfma_f32_16x16x32_bf16 v[86:89], v[150:153], v[170:173], v[162:165]
	s_nop 2
	ds_read_b64_tr_b16 v[162:163], v196 offset:18528
	ds_read_b64_tr_b16 v[164:165], v196 offset:21088
	v_mfma_f32_16x16x32_bf16 v[78:81], v[150:153], v[246:249], v[154:157]
	s_waitcnt lgkmcnt(2)
	v_mfma_f32_16x16x32_bf16 v[74:77], v[158:161], v[170:173], v[182:185]
	v_mfma_f32_16x16x32_bf16 v[70:73], v[158:161], v[246:249], v[166:169]
	s_waitcnt lgkmcnt(0)
	v_mfma_f32_16x16x32_bf16 v[66:69], v[162:165], v[170:173], v[178:181]
	v_mfma_f32_16x16x32_bf16 v[62:65], v[162:165], v[246:249], v[174:177]
	s_setprio 0
	s_branch .LBB0_797

; #define LAS __attribute__((address_space(3)))
; __device__ __forceinline__ float ex2(float x) { return __builtin_amdgcn_exp2f(x); }
; __device__ __forceinline__ f32x4 mfma16(bf16x8 a, bf16x8 b, f32x4 c) { return __builtin_amdgcn_mfma_f32_16x16x32_bf16(a, b, c, 0, 0, 0); }
;   __device__ __forceinline__ bf16_t* W() const { return (bf16_t*)(ws + WS_W); }
; template <int NT, int NKK, int NDT, int MODE, bool MASK> ...
;     ...
;   f32x4 s[NT][4];
;   __builtin_amdgcn_s_setprio(1);
; #pragma unroll
;   for (int t = 0; t < 4; ++t)
; #pragma unroll
;     for (int kk = 0; kk < NKK; ++kk) {
;       const bf16x8 kf = *(LAS const bf16x8*)(Kl + (16 * t + r) * KSTR + (32 * kk + 8 * lg) * 2);
; #pragma unroll
;       for (int j = 0; j < NT; ++j) s[j][t] = mfma16(kf, qf[j][kk], kk == 0 ? (f32x4){0.f, 0.f, 0.f, 0.f} : s[j][t]);
;     }
;   __builtin_amdgcn_s_setprio(0);
;   bf16x8 pf[NT][2];
; #pragma unroll
;   for (int j = 0; j < NT; ++j) {
;     float mx = -INFINITY;
; #pragma unroll
;     for (int t = 0; t < 4; ++t)
; #pragma unroll
;       for (int i = 0; i < 4; ++i) {
;         if (MASK) { const int kp = kpos0 + 16 * t + 4 * lg + i; if (!mask_ok<MODE>(tq[j], kp, W)) s[j][t][i] = -INFINITY; }
;         mx = fmaxf(mx, s[j][t][i]);
;       }
;     mx = max_x16_x32(mx);
;     if (__any(mx > m[j] + 8.0f / c)) {
;       const float mnew = fmaxf(m[j], mx);
;       const float ms2 = (mnew == -INFINITY) ? 0.f : mnew;
;       const float alpha = ex2((m[j] - ms2) * c);
;       m[j] = mnew; l[j] *= alpha;
; #pragma unroll
;       for (int dt = 0; dt < NDT; ++dt) o[j][dt] *= alpha;
;     }
;     const float mc = ((m[j] == -INFINITY) ? 0.f : m[j]) * c;
.LBB0_810:
	s_waitcnt lgkmcnt(0)
	s_barrier
	s_add_i32 s8, s69, 0xffffff81
	s_cmp_gt_i32 s8, s68
	s_cbranch_scc1 .LBB0_837
	s_sub_i32 s8, s69, 64
	s_cmp_gt_i32 s8, s59
	s_setprio 1
	v_add_u32_e32 v1, s73, v236
	s_waitcnt lgkmcnt(0)
	v_add_u32_e32 v94, v1, v237
	ds_read_b128 v[134:137], v94
	ds_read_b128 v[130:133], v94 offset:64
	ds_read_b128 v[126:129], v94 offset:128
	ds_read_b128 v[122:125], v94 offset:3328
	ds_read_b128 v[118:121], v94 offset:3392
	ds_read_b128 v[114:117], v94 offset:3456
	ds_read_b128 v[106:109], v94 offset:6656
	ds_read_b128 v[98:101], v94 offset:6720
	v_add_u32_e32 v201, v1, v238
	ds_read_b128 v[110:113], v94 offset:6784
	ds_read_b128 v[102:105], v201
	ds_read_b128 v[94:97], v201 offset:64
	s_mov_b64 s[20:21], -1
	v_add_f32_e32 v1, 0x4259535f, v220
	s_cbranch_scc1 .LBB0_828
	s_waitcnt lgkmcnt(10)
	v_mfma_f32_16x16x32_bf16 v[138:141], v[134:137], v[18:21], 0
	ds_read_b128 v[146:149], v201 offset:128
	v_mov_b32_e32 v234, 0x260
	v_mfma_f32_16x16x32_bf16 v[142:145], v[134:137], v[10:13], 0
	s_waitcnt lgkmcnt(10)
	v_mfma_f32_16x16x32_bf16 v[138:141], v[130:133], v[2:5], v[138:141]
	v_mov_b64_e32 v[222:223], v[220:221]
	v_mfma_f32_16x16x32_bf16 v[142:145], v[130:133], v[14:17], v[142:145]
	v_mov_b64_e32 v[224:225], v[218:219]
	s_waitcnt lgkmcnt(9)
	v_mfma_f32_16x16x32_bf16 v[182:185], v[126:129], v[6:9], v[138:141]
	v_mfma_f32_16x16x32_bf16 v[166:169], v[126:129], v[22:25], v[142:145]
	v_mov_b32_e32 v187, v220
	s_waitcnt lgkmcnt(8)
	v_mfma_f32_16x16x32_bf16 v[138:141], v[122:125], v[18:21], 0
	v_add_f32_e32 v158, 0x4259535f, v221
	v_mfma_f32_16x16x32_bf16 v[142:145], v[122:125], v[10:13], 0
	v_mul_f32_e32 v159, 0x3e16c740, v220
	s_waitcnt lgkmcnt(7)
	v_mfma_f32_16x16x32_bf16 v[138:141], v[118:121], v[2:5], v[138:141]
	v_cmp_neq_f32_e64 s[22:23], s81, v220
	v_mfma_f32_16x16x32_bf16 v[142:145], v[118:121], v[14:17], v[142:145]
	s_waitcnt lgkmcnt(6)
	v_mfma_f32_16x16x32_bf16 v[178:181], v[114:117], v[6:9], v[138:141]
	v_mfma_f32_16x16x32_bf16 v[154:157], v[114:117], v[22:25], v[142:145]
	v_cndmask_b32_e64 v159, 0, v159, s[22:23]
	s_waitcnt lgkmcnt(5)
	v_mfma_f32_16x16x32_bf16 v[138:141], v[106:109], v[18:21], 0
	v_mul_f32_e32 v160, 0x3e16c740, v221
	v_mfma_f32_16x16x32_bf16 v[142:145], v[106:109], v[10:13], 0
	v_cmp_neq_f32_e64 s[22:23], s81, v221
	v_max3_f32 v188, v182, s81, v183
	s_waitcnt lgkmcnt(4)
	v_mfma_f32_16x16x32_bf16 v[138:141], v[98:101], v[2:5], v[138:141]
	v_max3_f32 v188, v188, v184, v185
	v_mfma_f32_16x16x32_bf16 v[142:145], v[98:101], v[14:17], v[142:145]
	v_max3_f32 v189, v166, s81, v167
	s_waitcnt lgkmcnt(3)
	v_mfma_f32_16x16x32_bf16 v[174:177], v[110:113], v[6:9], v[138:141]
	v_cndmask_b32_e64 v160, 0, v160, s[22:23]
	v_max3_f32 v189, v189, v168, v169
	v_mfma_f32_16x16x32_bf16 v[150:153], v[110:113], v[22:25], v[142:145]
	s_waitcnt lgkmcnt(2)
	v_mfma_f32_16x16x32_bf16 v[138:141], v[102:105], v[18:21], 0
	v_mfma_f32_16x16x32_bf16 v[142:145], v[102:105], v[10:13], 0
	v_max3_f32 v188, v188, v178, v179
	s_waitcnt lgkmcnt(1)
	v_mfma_f32_16x16x32_bf16 v[138:141], v[94:97], v[2:5], v[138:141]
	v_max3_f32 v188, v188, v180, v181
	v_mfma_f32_16x16x32_bf16 v[142:145], v[94:97], v[14:17], v[142:145]
	v_max3_f32 v189, v189, v154, v155
	s_waitcnt lgkmcnt(0)
	v_mfma_f32_16x16x32_bf16 v[170:173], v[146:149], v[6:9], v[138:141]
	v_max3_f32 v189, v189, v156, v157
	v_mfma_f32_16x16x32_bf16 v[142:145], v[146:149], v[22:25], v[142:145]
	s_setprio 0
	s_nop 3
	v_max3_f32 v138, v188, v174, v175
	v_max3_f32 v138, v138, v176, v177
	v_max3_f32 v138, v138, v170, v171
	v_max3_f32 v138, v138, v172, v173
	v_mov_b32_e32 v139, v138
	s_nop 1
	v_permlane16_swap_b32_e32 v138, v139
	v_max_f32_e32 v138, v138, v139
	v_mov_b32_e32 v139, v138
	s_nop 1
	v_permlane32_swap_b32_e32 v138, v139
	v_max_f32_e32 v186, v138, v139
	v_cmp_gt_f32_e32 vcc, v186, v1
	s_cbranch_vccz .LBB0_814
	v_max_f32_e32 v138, v186, v186
	v_max_f32_e32 v139, v220, v220
	v_max_f32_e32 v222, v139, v138
	v_cmp_neq_f32_e32 vcc, s81, v222
	v_mov_b32_e32 v223, v221
	v_mov_b32_e32 v225, v219
	v_cndmask_b32_e32 v138, 0, v222, vcc
	v_sub_f32_e32 v138, v220, v138
	v_mul_f32_e32 v138, 0x3e16c740, v138
	v_exp_f32_e32 v138, v138
	v_mov_b32_e32 v187, v222
	v_mul_f32_e32 v224, v218, v138
	v_pk_mul_f32 v[92:93], v[92:93], v[138:139] op_sel_hi:[1,0]
	v_pk_mul_f32 v[90:91], v[90:91], v[138:139] op_sel_hi:[1,0]
	v_pk_mul_f32 v[88:89], v[88:89], v[138:139] op_sel_hi:[1,0]
	v_pk_mul_f32 v[86:87], v[86:87], v[138:139] op_sel_hi:[1,0]
	v_pk_mul_f32 v[76:77], v[76:77], v[138:139] op_sel_hi:[1,0]
	v_pk_mul_f32 v[74:75], v[74:75], v[138:139] op_sel_hi:[1,0]
	v_pk_mul_f32 v[68:69], v[68:69], v[138:139] op_sel_hi:[1,0]
	v_pk_mul_f32 v[66:67], v[66:67], v[138:139] op_sel_hi:[1,0]
	v_mul_f32_e32 v159, 0x3e16c740, v187
	v_cmp_neq_f32_e32 vcc, s81, v187
	s_nop 1
	v_cndmask_b32_e32 v159, 0, v159, vcc

; __device__ __forceinline__ float ex2(float x) { return __builtin_amdgcn_exp2f(x); }
; __device__ __forceinline__ f32x4 mfma16(bf16x8 a, bf16x8 b, f32x4 c) { return __builtin_amdgcn_mfma_f32_16x16x32_bf16(a, b, c, 0, 0, 0); }
; __device__ __forceinline__ s16x4 ds_tr(LAS const unsigned char* p) { return __builtin_bit_cast(s16x4, __builtin_amdgcn_ds_read_tr16_b64_v4i16((LAS v4i16_t*)p)); }
; template <int NT, int NKK, int NDT, int MODE, bool MASK> ...
;     ...
;     const float mc = ((m[j] == -INFINITY) ? 0.f : m[j]) * c;
;     float p[4][4], ps = 0.f;
; #pragma unroll
;     for (int t = 0; t < 4; ++t)
; #pragma unroll
;       for (int i = 0; i < 4; ++i) { p[t][i] = ex2(s[j][t][i] * c - mc); ps += p[t][i]; }
;     l[j] += ps;
;     pf[j][0] = pack8(p[0], p[1]); pf[j][1] = pack8(p[2], p[3]);
;   }
;   __builtin_amdgcn_s_setprio(1);
; #pragma unroll
;   for (int st = 0; st < 2; ++st)
; #pragma unroll
;     for (int dt = 0; dt < NDT; ++dt) {
;       const s16x4 v0 = ds_tr(Vl + (32 * st + 4 * lg + vq) * VSTR + (16 * dt + 4 * vp) * 2);
;       const s16x4 v1 = ds_tr(Vl + (32 * st + 16 + 4 * lg + vq) * VSTR + (16 * dt + 4 * vp) * 2);
;       const bf16x8 vf = (bf16x8){v0[0], v0[1], v0[2], v0[3], v1[0], v1[1], v1[2], v1[3]};
; #pragma unroll
;       for (int j = 0; j < NT; ++j) o[j][dt] = mfma16(vf, pf[j][st], o[j][dt]);
;     }
.LBB0_826:
.LBB0_827:
	v_cvt_pk_bf16_f32 v173, v196, v173
	v_cvt_pk_bf16_f32 v172, v232, v228
	v_cvt_pk_bf16_f32 v228, v205, v207
	v_fma_f32 v166, v166, s88, -v160
	v_exp_f32_e32 v166, v166
	v_fma_f32 v167, v167, s88, -v160
	v_exp_f32_e32 v167, v167
	v_fma_f32 v168, v168, s88, -v160
	v_exp_f32_e32 v168, v168
	v_fma_f32 v169, v169, s88, -v160
	v_exp_f32_e32 v169, v169
	v_fma_f32 v154, v154, s88, -v160
	v_exp_f32_e32 v154, v154
	v_fma_f32 v155, v155, s88, -v160
	v_add_f32_e32 v197, v167, v166
	v_exp_f32_e32 v155, v155
	v_fma_f32 v156, v156, s88, -v160
	v_add_f32_e32 v197, v168, v197
	v_exp_f32_e32 v156, v156
	v_fma_f32 v157, v157, s88, -v160
	v_add_f32_e32 v197, v169, v197
	v_exp_f32_e32 v157, v157
	v_fma_f32 v150, v150, s88, -v160
	v_add_f32_e32 v197, v154, v197
	v_exp_f32_e32 v150, v150
	v_fma_f32 v151, v151, s88, -v160
	v_add_f32_e32 v197, v155, v197
	v_exp_f32_e32 v151, v151
	v_fma_f32 v152, v152, s88, -v160
	v_add_f32_e32 v197, v156, v197
	v_exp_f32_e32 v152, v152
	v_fma_f32 v153, v153, s88, -v160
	v_add_f32_e32 v197, v157, v197
	v_exp_f32_e32 v153, v153
	v_fma_f32 v142, v142, s88, -v160
	v_add_f32_e32 v197, v150, v197
	v_exp_f32_e32 v198, v142
	v_fma_f32 v142, v143, s88, -v160
	v_add_f32_e32 v197, v151, v197
	v_exp_f32_e32 v199, v142
	v_fma_f32 v142, v144, s88, -v160
	v_add_f32_e32 v197, v152, v197
	v_exp_f32_e32 v205, v142
	v_fma_f32 v142, v145, s88, -v160
	v_add_f32_e32 v197, v153, v197
	v_exp_f32_e32 v196, v142
	v_add_f32_e32 v142, v198, v197
	v_add_f32_e32 v142, v199, v142
	v_add_f32_e32 v142, v205, v142
	v_add_f32_e32 v142, v196, v142
	v_add_f32_e32 v225, v225, v142
	v_cvt_pk_bf16_f32 v142, v166, v167
	v_cvt_pk_bf16_f32 v143, v168, v169
	v_cvt_pk_bf16_f32 v144, v154, v155
	v_cvt_pk_bf16_f32 v145, v156, v157
	v_cvt_pk_bf16_f32 v170, v252, v231
	v_cvt_pk_bf16_f32 v171, v229, v230
	v_cvt_pk_bf16_f32 v229, v246, v247
	v_cvt_pk_bf16_f32 v230, v248, v249
	v_cvt_pk_bf16_f32 v231, v250, v251
	v_cvt_pk_bf16_f32 v246, v150, v151
	v_cvt_pk_bf16_f32 v247, v152, v153
	v_cvt_pk_bf16_f32 v248, v198, v199
	v_cvt_pk_bf16_f32 v249, v205, v196
	s_setprio 1
	v_add3_u32 v196, s73, v240, v239
	ds_read_b64_tr_b16 v[152:153], v196 offset:15872
	ds_read_b64_tr_b16 v[150:151], v196 offset:13312
	ds_read_b64_tr_b16 v[154:155], v196 offset:13344
	ds_read_b64_tr_b16 v[156:157], v196 offset:15904
	ds_read_b64_tr_b16 v[166:167], v196 offset:13376
	ds_read_b64_tr_b16 v[168:169], v196 offset:15936
	s_mov_b64 s[20:21], 0
	s_waitcnt lgkmcnt(4)
	v_mfma_f32_16x16x32_bf16 v[158:161], v[150:153], v[228:231], v[90:93]
	v_mfma_f32_16x16x32_bf16 v[150:153], v[150:153], v[142:145], v[82:85]
	v_mov_b64_e32 v[218:219], v[224:225]
	s_waitcnt lgkmcnt(0)
	v_mfma_f32_16x16x32_bf16 v[182:185], v[166:169], v[228:231], v[74:77]
	s_nop 2
	ds_read_b64_tr_b16 v[146:147], v196 offset:13408
	ds_read_b64_tr_b16 v[148:149], v196 offset:15968
	v_mfma_f32_16x16x32_bf16 v[162:165], v[154:157], v[228:231], v[86:89]
	v_mov_b64_e32 v[220:221], v[222:223]
	v_mfma_f32_16x16x32_bf16 v[154:157], v[154:157], v[142:145], v[78:81]
	v_mfma_f32_16x16x32_bf16 v[166:169], v[166:169], v[142:145], v[70:73]
	s_waitcnt lgkmcnt(0)
	v_mfma_f32_16x16x32_bf16 v[174:177], v[146:149], v[142:145], v[62:65]
	ds_read_b64_tr_b16 v[142:143], v196 offset:18432
	ds_read_b64_tr_b16 v[144:145], v196 offset:20992
	v_mfma_f32_16x16x32_bf16 v[178:181], v[146:149], v[228:231], v[66:69]
	s_waitcnt lgkmcnt(0)
	v_mfma_f32_16x16x32_bf16 v[90:93], v[142:145], v[170:173], v[158:161]
	v_mfma_f32_16x16x32_bf16 v[82:85], v[142:145], v[246:249], v[150:153]
	s_nop 2
	ds_read_b64_tr_b16 v[150:151], v196 offset:18464
	ds_read_b64_tr_b16 v[152:153], v196 offset:21024
	ds_read_b64_tr_b16 v[158:159], v196 offset:18496
	ds_read_b64_tr_b16 v[160:161], v196 offset:21056
	s_waitcnt lgkmcnt(2)
	v_mfma_f32_16x16x32_bf16 v[86:89], v[150:153], v[170:173], v[162:165]
	s_nop 2
	ds_read_b64_tr_b16 v[162:163], v196 offset:18528
	ds_read_b64_tr_b16 v[164:165], v196 offset:21088
	v_mfma_f32_16x16x32_bf16 v[78:81], v[150:153], v[246:249], v[154:157]
	s_waitcnt lgkmcnt(2)
	v_mfma_f32_16x16x32_bf16 v[74:77], v[158:161], v[170:173], v[182:185]
	v_mfma_f32_16x16x32_bf16 v[70:73], v[158:161], v[246:249], v[166:169]
	s_waitcnt lgkmcnt(0)
	v_mfma_f32_16x16x32_bf16 v[66:69], v[162:165], v[170:173], v[178:181]
	v_mfma_f32_16x16x32_bf16 v[62:65], v[162:165], v[246:249], v[174:177]
	s_setprio 0
	s_branch .LBB0_837

; #define LAS __attribute__((address_space(3)))
; __device__ __forceinline__ float ex2(float x) { return __builtin_amdgcn_exp2f(x); }
; __device__ __forceinline__ f32x4 mfma16(bf16x8 a, bf16x8 b, f32x4 c) { return __builtin_amdgcn_mfma_f32_16x16x32_bf16(a, b, c, 0, 0, 0); }
;   __device__ __forceinline__ bf16_t* W() const { return (bf16_t*)(ws + WS_W); }
; template <int NT, int NKK, int NDT, int MODE, bool MASK> ...
;     ...
;   f32x4 s[NT][4];
;   __builtin_amdgcn_s_setprio(1);
; #pragma unroll
;   for (int t = 0; t < 4; ++t)
; #pragma unroll
;     for (int kk = 0; kk < NKK; ++kk) {
;       const bf16x8 kf = *(LAS const bf16x8*)(Kl + (16 * t + r) * KSTR + (32 * kk + 8 * lg) * 2);
; #pragma unroll
;       for (int j = 0; j < NT; ++j) s[j][t] = mfma16(kf, qf[j][kk], kk == 0 ? (f32x4){0.f, 0.f, 0.f, 0.f} : s[j][t]);
;     }
;   __builtin_amdgcn_s_setprio(0);
;   bf16x8 pf[NT][2];
; #pragma unroll
;   for (int j = 0; j < NT; ++j) {
;     float mx = -INFINITY;
; #pragma unroll
;     for (int t = 0; t < 4; ++t)
; #pragma unroll
;       for (int i = 0; i < 4; ++i) {
;         if (MASK) { const int kp = kpos0 + 16 * t + 4 * lg + i; if (!mask_ok<MODE>(tq[j], kp, W)) s[j][t][i] = -INFINITY; }
;         mx = fmaxf(mx, s[j][t][i]);
;       }
;     mx = max_x16_x32(mx);
;     if (__any(mx > m[j] + 8.0f / c)) {
;       const float mnew = fmaxf(m[j], mx);
;       const float ms2 = (mnew == -INFINITY) ? 0.f : mnew;
;       const float alpha = ex2((m[j] - ms2) * c);
;       m[j] = mnew; l[j] *= alpha;
; #pragma unroll
;       for (int dt = 0; dt < NDT; ++dt) o[j][dt] *= alpha;
;     }
;     const float mc = ((m[j] == -INFINITY) ? 0.f : m[j]) * c;
.LBB0_850:
	s_waitcnt lgkmcnt(0)
	s_barrier
	s_sub_i32 s8, s69, 63
	s_cmp_gt_i32 s8, s68
	s_cbranch_scc1 .LBB0_877
	s_cmp_gt_i32 s69, s59
	s_setprio 1
	v_add_u32_e32 v1, s71, v236
	s_waitcnt lgkmcnt(0)
	v_add_u32_e32 v94, v1, v237
	ds_read_b128 v[134:137], v94
	ds_read_b128 v[130:133], v94 offset:64
	ds_read_b128 v[126:129], v94 offset:128
	ds_read_b128 v[122:125], v94 offset:3328
	ds_read_b128 v[118:121], v94 offset:3392
	ds_read_b128 v[114:117], v94 offset:3456
	ds_read_b128 v[106:109], v94 offset:6656
	ds_read_b128 v[98:101], v94 offset:6720
	v_add_u32_e32 v201, v1, v238
	ds_read_b128 v[110:113], v94 offset:6784
	ds_read_b128 v[102:105], v201
	ds_read_b128 v[94:97], v201 offset:64
	s_mov_b64 s[20:21], -1
	v_add_f32_e32 v1, 0x4259535f, v220
	s_cbranch_scc1 .LBB0_868
	s_waitcnt lgkmcnt(10)
	v_mfma_f32_16x16x32_bf16 v[138:141], v[134:137], v[18:21], 0
	ds_read_b128 v[146:149], v201 offset:128
	v_mov_b32_e32 v234, 0x260
	v_mfma_f32_16x16x32_bf16 v[142:145], v[134:137], v[10:13], 0
	s_waitcnt lgkmcnt(10)
	v_mfma_f32_16x16x32_bf16 v[138:141], v[130:133], v[2:5], v[138:141]
	v_mov_b64_e32 v[222:223], v[220:221]
	v_mfma_f32_16x16x32_bf16 v[142:145], v[130:133], v[14:17], v[142:145]
	v_mov_b64_e32 v[224:225], v[218:219]
	s_waitcnt lgkmcnt(9)
	v_mfma_f32_16x16x32_bf16 v[182:185], v[126:129], v[6:9], v[138:141]
	v_mfma_f32_16x16x32_bf16 v[166:169], v[126:129], v[22:25], v[142:145]
	v_mov_b32_e32 v187, v220
	s_waitcnt lgkmcnt(8)
	v_mfma_f32_16x16x32_bf16 v[138:141], v[122:125], v[18:21], 0
	v_add_f32_e32 v158, 0x4259535f, v221
	v_mfma_f32_16x16x32_bf16 v[142:145], v[122:125], v[10:13], 0
	v_mul_f32_e32 v159, 0x3e16c740, v220
	s_waitcnt lgkmcnt(7)
	v_mfma_f32_16x16x32_bf16 v[138:141], v[118:121], v[2:5], v[138:141]
	v_cmp_neq_f32_e64 s[22:23], s81, v220
	v_mfma_f32_16x16x32_bf16 v[142:145], v[118:121], v[14:17], v[142:145]
	s_waitcnt lgkmcnt(6)
	v_mfma_f32_16x16x32_bf16 v[178:181], v[114:117], v[6:9], v[138:141]
	v_mfma_f32_16x16x32_bf16 v[154:157], v[114:117], v[22:25], v[142:145]
	v_cndmask_b32_e64 v159, 0, v159, s[22:23]
	s_waitcnt lgkmcnt(5)
	v_mfma_f32_16x16x32_bf16 v[138:141], v[106:109], v[18:21], 0
	v_mul_f32_e32 v160, 0x3e16c740, v221
	v_mfma_f32_16x16x32_bf16 v[142:145], v[106:109], v[10:13], 0
	v_cmp_neq_f32_e64 s[22:23], s81, v221
	v_max3_f32 v188, v182, s81, v183
	s_waitcnt lgkmcnt(4)
	v_mfma_f32_16x16x32_bf16 v[138:141], v[98:101], v[2:5], v[138:141]
	v_max3_f32 v188, v188, v184, v185
	v_mfma_f32_16x16x32_bf16 v[142:145], v[98:101], v[14:17], v[142:145]
	v_max3_f32 v189, v166, s81, v167
	s_waitcnt lgkmcnt(3)
	v_mfma_f32_16x16x32_bf16 v[174:177], v[110:113], v[6:9], v[138:141]
	v_cndmask_b32_e64 v160, 0, v160, s[22:23]
	v_max3_f32 v189, v189, v168, v169
	v_mfma_f32_16x16x32_bf16 v[150:153], v[110:113], v[22:25], v[142:145]
	s_waitcnt lgkmcnt(2)
	v_mfma_f32_16x16x32_bf16 v[138:141], v[102:105], v[18:21], 0
	v_mfma_f32_16x16x32_bf16 v[142:145], v[102:105], v[10:13], 0
	v_max3_f32 v188, v188, v178, v179
	s_waitcnt lgkmcnt(1)
	v_mfma_f32_16x16x32_bf16 v[138:141], v[94:97], v[2:5], v[138:141]
	v_max3_f32 v188, v188, v180, v181
	v_mfma_f32_16x16x32_bf16 v[142:145], v[94:97], v[14:17], v[142:145]
	v_max3_f32 v189, v189, v154, v155
	s_waitcnt lgkmcnt(0)
	v_mfma_f32_16x16x32_bf16 v[170:173], v[146:149], v[6:9], v[138:141]
	v_max3_f32 v189, v189, v156, v157
	v_mfma_f32_16x16x32_bf16 v[142:145], v[146:149], v[22:25], v[142:145]
	s_setprio 0
	s_nop 3
	v_max3_f32 v138, v188, v174, v175
	v_max3_f32 v138, v138, v176, v177
	v_max3_f32 v138, v138, v170, v171
	v_max3_f32 v138, v138, v172, v173
	v_mov_b32_e32 v139, v138
	s_nop 1
	v_permlane16_swap_b32_e32 v138, v139
	v_max_f32_e32 v138, v138, v139
	v_mov_b32_e32 v139, v138
	s_nop 1
	v_permlane32_swap_b32_e32 v138, v139
	v_max_f32_e32 v186, v138, v139
	v_cmp_gt_f32_e32 vcc, v186, v1
	s_cbranch_vccz .LBB0_854
	v_max_f32_e32 v138, v186, v186
	v_max_f32_e32 v139, v220, v220
	v_max_f32_e32 v222, v139, v138
	v_cmp_neq_f32_e32 vcc, s81, v222
	v_mov_b32_e32 v223, v221
	v_mov_b32_e32 v225, v219
	v_cndmask_b32_e32 v138, 0, v222, vcc
	v_sub_f32_e32 v138, v220, v138
	v_mul_f32_e32 v138, 0x3e16c740, v138
	v_exp_f32_e32 v138, v138
	v_mov_b32_e32 v187, v222
	v_mul_f32_e32 v224, v218, v138
	v_pk_mul_f32 v[92:93], v[92:93], v[138:139] op_sel_hi:[1,0]
	v_pk_mul_f32 v[90:91], v[90:91], v[138:139] op_sel_hi:[1,0]
	v_pk_mul_f32 v[88:89], v[88:89], v[138:139] op_sel_hi:[1,0]
	v_pk_mul_f32 v[86:87], v[86:87], v[138:139] op_sel_hi:[1,0]
	v_pk_mul_f32 v[76:77], v[76:77], v[138:139] op_sel_hi:[1,0]
	v_pk_mul_f32 v[74:75], v[74:75], v[138:139] op_sel_hi:[1,0]
	v_pk_mul_f32 v[68:69], v[68:69], v[138:139] op_sel_hi:[1,0]
	v_pk_mul_f32 v[66:67], v[66:67], v[138:139] op_sel_hi:[1,0]
	v_mul_f32_e32 v159, 0x3e16c740, v187
	v_cmp_neq_f32_e32 vcc, s81, v187
	s_nop 1
	v_cndmask_b32_e32 v159, 0, v159, vcc

; #define LAS __attribute__((address_space(3)))
; __device__ __forceinline__ float ex2(float x) { return __builtin_amdgcn_exp2f(x); }
; __device__ __forceinline__ f32x4 mfma16(bf16x8 a, bf16x8 b, f32x4 c) { return __builtin_amdgcn_mfma_f32_16x16x32_bf16(a, b, c, 0, 0, 0); }
;   __device__ __forceinline__ bf16_t* W() const { return (bf16_t*)(ws + WS_W); }
; template <int NT, int NKK, int NDT, int MODE, bool MASK> ...
;     ...
;   f32x4 s[NT][4];
;   __builtin_amdgcn_s_setprio(1);
; #pragma unroll
;   for (int t = 0; t < 4; ++t)
; #pragma unroll
;     for (int kk = 0; kk < NKK; ++kk) {
;       const bf16x8 kf = *(LAS const bf16x8*)(Kl + (16 * t + r) * KSTR + (32 * kk + 8 * lg) * 2);
; #pragma unroll
;       for (int j = 0; j < NT; ++j) s[j][t] = mfma16(kf, qf[j][kk], kk == 0 ? (f32x4){0.f, 0.f, 0.f, 0.f} : s[j][t]);
;     }
;   __builtin_amdgcn_s_setprio(0);
;   bf16x8 pf[NT][2];
; #pragma unroll
;   for (int j = 0; j < NT; ++j) {
;     float mx = -INFINITY;
; #pragma unroll
;     for (int t = 0; t < 4; ++t)
; #pragma unroll
;       for (int i = 0; i < 4; ++i) {
;         if (MASK) { const int kp = kpos0 + 16 * t + 4 * lg + i; if (!mask_ok<MODE>(tq[j], kp, W)) s[j][t][i] = -INFINITY; }
;         mx = fmaxf(mx, s[j][t][i]);
;       }
;     mx = max_x16_x32(mx);
;     if (__any(mx > m[j] + 8.0f / c)) {
;       const float mnew = fmaxf(m[j], mx);
;       const float ms2 = (mnew == -INFINITY) ? 0.f : mnew;
;       const float alpha = ex2((m[j] - ms2) * c);
;       m[j] = mnew; l[j] *= alpha;
; #pragma unroll
;       for (int dt = 0; dt < NDT; ++dt) o[j][dt] *= alpha;
;     }
;     const float mc = ((m[j] == -INFINITY) ? 0.f : m[j]) * c;
.LBB0_941:
	s_waitcnt lgkmcnt(0)
	s_barrier
	s_add_i32 s8, s43, 0xffffff41
	s_cmp_gt_i32 s8, s40
	s_cbranch_scc1 .LBB0_970
	s_add_i32 s8, s43, 0xffffff80
	s_cmp_gt_i32 s8, s25
	s_setprio 1
	v_add_u32_e32 v1, s45, v236
	s_waitcnt lgkmcnt(0)
	v_add_u32_e32 v94, v1, v237
	ds_read_b128 v[134:137], v94
	ds_read_b128 v[130:133], v94 offset:64
	ds_read_b128 v[126:129], v94 offset:128
	ds_read_b128 v[122:125], v94 offset:3328
	ds_read_b128 v[118:121], v94 offset:3392
	ds_read_b128 v[114:117], v94 offset:3456
	ds_read_b128 v[106:109], v94 offset:6656
	ds_read_b128 v[98:101], v94 offset:6720
	v_add_u32_e32 v201, v1, v238
	ds_read_b128 v[110:113], v94 offset:6784
	ds_read_b128 v[102:105], v201
	ds_read_b128 v[94:97], v201 offset:64
	s_mov_b64 s[20:21], -1
	v_add_f32_e32 v1, 0x4259535f, v220
	s_cbranch_scc1 .LBB0_961
	s_waitcnt lgkmcnt(10)
	v_mfma_f32_16x16x32_bf16 v[138:141], v[134:137], v[18:21], 0
	ds_read_b128 v[146:149], v201 offset:128
	v_mov_b32_e32 v234, 0x260
	v_mfma_f32_16x16x32_bf16 v[142:145], v[134:137], v[10:13], 0
	s_waitcnt lgkmcnt(10)
	v_mfma_f32_16x16x32_bf16 v[138:141], v[130:133], v[2:5], v[138:141]
	v_mov_b64_e32 v[222:223], v[220:221]
	v_mfma_f32_16x16x32_bf16 v[142:145], v[130:133], v[14:17], v[142:145]
	v_mov_b64_e32 v[224:225], v[218:219]
	s_waitcnt lgkmcnt(9)
	v_mfma_f32_16x16x32_bf16 v[182:185], v[126:129], v[6:9], v[138:141]
	v_mfma_f32_16x16x32_bf16 v[166:169], v[126:129], v[22:25], v[142:145]
	v_mov_b32_e32 v187, v220
	s_waitcnt lgkmcnt(8)
	v_mfma_f32_16x16x32_bf16 v[138:141], v[122:125], v[18:21], 0
	v_add_f32_e32 v158, 0x4259535f, v221
	v_mfma_f32_16x16x32_bf16 v[142:145], v[122:125], v[10:13], 0
	v_mul_f32_e32 v159, 0x3e16c740, v220
	s_waitcnt lgkmcnt(7)
	v_mfma_f32_16x16x32_bf16 v[138:141], v[118:121], v[2:5], v[138:141]
	v_cmp_neq_f32_e64 s[22:23], s81, v220
	v_mfma_f32_16x16x32_bf16 v[142:145], v[118:121], v[14:17], v[142:145]
	s_waitcnt lgkmcnt(6)
	v_mfma_f32_16x16x32_bf16 v[178:181], v[114:117], v[6:9], v[138:141]
	v_mfma_f32_16x16x32_bf16 v[154:157], v[114:117], v[22:25], v[142:145]
	v_cndmask_b32_e64 v159, 0, v159, s[22:23]
	s_waitcnt lgkmcnt(5)
	v_mfma_f32_16x16x32_bf16 v[138:141], v[106:109], v[18:21], 0
	v_mul_f32_e32 v160, 0x3e16c740, v221
	v_mfma_f32_16x16x32_bf16 v[142:145], v[106:109], v[10:13], 0
	v_cmp_neq_f32_e64 s[22:23], s81, v221
	v_max3_f32 v188, v182, s81, v183
	s_waitcnt lgkmcnt(4)
	v_mfma_f32_16x16x32_bf16 v[138:141], v[98:101], v[2:5], v[138:141]
	v_max3_f32 v188, v188, v184, v185
	v_mfma_f32_16x16x32_bf16 v[142:145], v[98:101], v[14:17], v[142:145]
	v_max3_f32 v189, v166, s81, v167
	s_waitcnt lgkmcnt(3)
	v_mfma_f32_16x16x32_bf16 v[174:177], v[110:113], v[6:9], v[138:141]
	v_cndmask_b32_e64 v160, 0, v160, s[22:23]
	v_max3_f32 v189, v189, v168, v169
	v_mfma_f32_16x16x32_bf16 v[150:153], v[110:113], v[22:25], v[142:145]
	s_waitcnt lgkmcnt(2)
	v_mfma_f32_16x16x32_bf16 v[138:141], v[102:105], v[18:21], 0
	v_mfma_f32_16x16x32_bf16 v[142:145], v[102:105], v[10:13], 0
	v_max3_f32 v188, v188, v178, v179
	s_waitcnt lgkmcnt(1)
	v_mfma_f32_16x16x32_bf16 v[138:141], v[94:97], v[2:5], v[138:141]
	v_max3_f32 v188, v188, v180, v181
	v_mfma_f32_16x16x32_bf16 v[142:145], v[94:97], v[14:17], v[142:145]
	v_max3_f32 v189, v189, v154, v155
	s_waitcnt lgkmcnt(0)
	v_mfma_f32_16x16x32_bf16 v[170:173], v[146:149], v[6:9], v[138:141]
	v_max3_f32 v189, v189, v156, v157
	v_mfma_f32_16x16x32_bf16 v[142:145], v[146:149], v[22:25], v[142:145]
	s_setprio 0
	s_nop 3
	v_max3_f32 v138, v188, v174, v175
	v_max3_f32 v138, v138, v176, v177
	v_max3_f32 v138, v138, v170, v171
	v_max3_f32 v138, v138, v172, v173
	v_mov_b32_e32 v139, v138
	s_nop 1
	v_permlane16_swap_b32_e32 v138, v139
	v_max_f32_e32 v138, v138, v139
	v_mov_b32_e32 v139, v138
	s_nop 1
	v_permlane32_swap_b32_e32 v138, v139
	v_max_f32_e32 v186, v138, v139
	v_cmp_gt_f32_e32 vcc, v186, v1
	s_cbranch_vccz .LBB0_945
	v_max_f32_e32 v138, v186, v186
	v_max_f32_e32 v139, v220, v220
	v_max_f32_e32 v222, v139, v138
	v_cmp_neq_f32_e32 vcc, s81, v222
	v_mov_b32_e32 v223, v221
	v_mov_b32_e32 v225, v219
	v_cndmask_b32_e32 v138, 0, v222, vcc
	v_sub_f32_e32 v138, v220, v138
	v_mul_f32_e32 v138, 0x3e16c740, v138
	v_exp_f32_e32 v138, v138
	v_mov_b32_e32 v187, v222
	v_mul_f32_e32 v224, v218, v138
	v_pk_mul_f32 v[92:93], v[92:93], v[138:139] op_sel_hi:[1,0]
	v_pk_mul_f32 v[90:91], v[90:91], v[138:139] op_sel_hi:[1,0]
	v_pk_mul_f32 v[88:89], v[88:89], v[138:139] op_sel_hi:[1,0]
	v_pk_mul_f32 v[86:87], v[86:87], v[138:139] op_sel_hi:[1,0]
	v_pk_mul_f32 v[76:77], v[76:77], v[138:139] op_sel_hi:[1,0]
	v_pk_mul_f32 v[74:75], v[74:75], v[138:139] op_sel_hi:[1,0]
	v_pk_mul_f32 v[68:69], v[68:69], v[138:139] op_sel_hi:[1,0]
	v_pk_mul_f32 v[66:67], v[66:67], v[138:139] op_sel_hi:[1,0]
	v_mul_f32_e32 v159, 0x3e16c740, v187
	v_cmp_neq_f32_e32 vcc, s81, v187
	s_nop 1
	v_cndmask_b32_e32 v159, 0, v159, vcc

; __device__ __forceinline__ float ex2(float x) { return __builtin_amdgcn_exp2f(x); }
; __device__ __forceinline__ f32x4 mfma16(bf16x8 a, bf16x8 b, f32x4 c) { return __builtin_amdgcn_mfma_f32_16x16x32_bf16(a, b, c, 0, 0, 0); }
; __device__ __forceinline__ s16x4 ds_tr(LAS const unsigned char* p) { return __builtin_bit_cast(s16x4, __builtin_amdgcn_ds_read_tr16_b64_v4i16((LAS v4i16_t*)p)); }
; template <int NT, int NKK, int NDT, int MODE, bool MASK> ...
;     ...
;     const float mc = ((m[j] == -INFINITY) ? 0.f : m[j]) * c;
;     float p[4][4], ps = 0.f;
; #pragma unroll
;     for (int t = 0; t < 4; ++t)
; #pragma unroll
;       for (int i = 0; i < 4; ++i) { p[t][i] = ex2(s[j][t][i] * c - mc); ps += p[t][i]; }
;     l[j] += ps;
;     pf[j][0] = pack8(p[0], p[1]); pf[j][1] = pack8(p[2], p[3]);
;   }
;   __builtin_amdgcn_s_setprio(1);
; #pragma unroll
;   for (int st = 0; st < 2; ++st)
; #pragma unroll
;     for (int dt = 0; dt < NDT; ++dt) {
;       const s16x4 v0 = ds_tr(Vl + (32 * st + 4 * lg + vq) * VSTR + (16 * dt + 4 * vp) * 2);
;       const s16x4 v1 = ds_tr(Vl + (32 * st + 16 + 4 * lg + vq) * VSTR + (16 * dt + 4 * vp) * 2);
;       const bf16x8 vf = (bf16x8){v0[0], v0[1], v0[2], v0[3], v1[0], v1[1], v1[2], v1[3]};
; #pragma unroll
;       for (int j = 0; j < NT; ++j) o[j][dt] = mfma16(vf, pf[j][st], o[j][dt]);
;     }
.LBB0_959:
.LBB0_960:
	v_cvt_pk_bf16_f32 v173, v196, v173
	v_cvt_pk_bf16_f32 v172, v232, v228
	v_cvt_pk_bf16_f32 v228, v205, v207
	v_fma_f32 v166, v166, s88, -v160
	v_exp_f32_e32 v166, v166
	v_fma_f32 v167, v167, s88, -v160
	v_exp_f32_e32 v167, v167
	v_fma_f32 v168, v168, s88, -v160
	v_exp_f32_e32 v168, v168
	v_fma_f32 v169, v169, s88, -v160
	v_exp_f32_e32 v169, v169
	v_fma_f32 v154, v154, s88, -v160
	v_exp_f32_e32 v154, v154
	v_fma_f32 v155, v155, s88, -v160
	v_add_f32_e32 v197, v167, v166
	v_exp_f32_e32 v155, v155
	v_fma_f32 v156, v156, s88, -v160
	v_add_f32_e32 v197, v168, v197
	v_exp_f32_e32 v156, v156
	v_fma_f32 v157, v157, s88, -v160
	v_add_f32_e32 v197, v169, v197
	v_exp_f32_e32 v157, v157
	v_fma_f32 v150, v150, s88, -v160
	v_add_f32_e32 v197, v154, v197
	v_exp_f32_e32 v150, v150
	v_fma_f32 v151, v151, s88, -v160
	v_add_f32_e32 v197, v155, v197
	v_exp_f32_e32 v151, v151
	v_fma_f32 v152, v152, s88, -v160
	v_add_f32_e32 v197, v156, v197
	v_exp_f32_e32 v152, v152
	v_fma_f32 v153, v153, s88, -v160
	v_add_f32_e32 v197, v157, v197
	v_exp_f32_e32 v153, v153
	v_fma_f32 v142, v142, s88, -v160
	v_add_f32_e32 v197, v150, v197
	v_exp_f32_e32 v198, v142
	v_fma_f32 v142, v143, s88, -v160
	v_add_f32_e32 v197, v151, v197
	v_exp_f32_e32 v199, v142
	v_fma_f32 v142, v144, s88, -v160
	v_add_f32_e32 v197, v152, v197
	v_exp_f32_e32 v205, v142
	v_fma_f32 v142, v145, s88, -v160
	v_add_f32_e32 v197, v153, v197
	v_exp_f32_e32 v196, v142
	v_add_f32_e32 v142, v198, v197
	v_add_f32_e32 v142, v199, v142
	v_add_f32_e32 v142, v205, v142
	v_add_f32_e32 v142, v196, v142
	v_add_f32_e32 v225, v225, v142
	v_cvt_pk_bf16_f32 v142, v166, v167
	v_cvt_pk_bf16_f32 v143, v168, v169
	v_cvt_pk_bf16_f32 v144, v154, v155
	v_cvt_pk_bf16_f32 v145, v156, v157
	v_cvt_pk_bf16_f32 v170, v252, v231
	v_cvt_pk_bf16_f32 v171, v229, v230
	v_cvt_pk_bf16_f32 v229, v246, v247
	v_cvt_pk_bf16_f32 v230, v248, v249
	v_cvt_pk_bf16_f32 v231, v250, v251
	v_cvt_pk_bf16_f32 v246, v150, v151
	v_cvt_pk_bf16_f32 v247, v152, v153
	v_cvt_pk_bf16_f32 v248, v198, v199
	v_cvt_pk_bf16_f32 v249, v205, v196
	s_setprio 1
	v_add3_u32 v196, s45, v240, v239
	ds_read_b64_tr_b16 v[152:153], v196 offset:15872
	ds_read_b64_tr_b16 v[150:151], v196 offset:13312
	ds_read_b64_tr_b16 v[154:155], v196 offset:13344
	ds_read_b64_tr_b16 v[156:157], v196 offset:15904
	ds_read_b64_tr_b16 v[166:167], v196 offset:13376
	ds_read_b64_tr_b16 v[168:169], v196 offset:15936
	s_mov_b64 s[20:21], 0
	s_waitcnt lgkmcnt(4)
	v_mfma_f32_16x16x32_bf16 v[158:161], v[150:153], v[228:231], v[90:93]
	v_mfma_f32_16x16x32_bf16 v[150:153], v[150:153], v[142:145], v[82:85]
	v_mov_b64_e32 v[218:219], v[224:225]
	s_waitcnt lgkmcnt(0)
	v_mfma_f32_16x16x32_bf16 v[182:185], v[166:169], v[228:231], v[74:77]
	s_nop 2
	ds_read_b64_tr_b16 v[146:147], v196 offset:13408
	ds_read_b64_tr_b16 v[148:149], v196 offset:15968
	v_mfma_f32_16x16x32_bf16 v[162:165], v[154:157], v[228:231], v[86:89]
	v_mov_b64_e32 v[220:221], v[222:223]
	v_mfma_f32_16x16x32_bf16 v[154:157], v[154:157], v[142:145], v[78:81]
	v_mfma_f32_16x16x32_bf16 v[166:169], v[166:169], v[142:145], v[70:73]
	s_waitcnt lgkmcnt(0)
	v_mfma_f32_16x16x32_bf16 v[174:177], v[146:149], v[142:145], v[62:65]
	ds_read_b64_tr_b16 v[142:143], v196 offset:18432
	ds_read_b64_tr_b16 v[144:145], v196 offset:20992
	v_mfma_f32_16x16x32_bf16 v[178:181], v[146:149], v[228:231], v[66:69]
	s_waitcnt lgkmcnt(0)
	v_mfma_f32_16x16x32_bf16 v[90:93], v[142:145], v[170:173], v[158:161]
	v_mfma_f32_16x16x32_bf16 v[82:85], v[142:145], v[246:249], v[150:153]
	s_nop 2
	ds_read_b64_tr_b16 v[150:151], v196 offset:18464
	ds_read_b64_tr_b16 v[152:153], v196 offset:21024
	ds_read_b64_tr_b16 v[158:159], v196 offset:18496
	ds_read_b64_tr_b16 v[160:161], v196 offset:21056
	s_waitcnt lgkmcnt(2)
	v_mfma_f32_16x16x32_bf16 v[86:89], v[150:153], v[170:173], v[162:165]
	s_nop 2
	ds_read_b64_tr_b16 v[162:163], v196 offset:18528
	ds_read_b64_tr_b16 v[164:165], v196 offset:21088
	v_mfma_f32_16x16x32_bf16 v[78:81], v[150:153], v[246:249], v[154:157]
	s_waitcnt lgkmcnt(2)
	v_mfma_f32_16x16x32_bf16 v[74:77], v[158:161], v[170:173], v[182:185]
	v_mfma_f32_16x16x32_bf16 v[70:73], v[158:161], v[246:249], v[166:169]
	s_waitcnt lgkmcnt(0)
	v_mfma_f32_16x16x32_bf16 v[66:69], v[162:165], v[170:173], v[178:181]
	v_mfma_f32_16x16x32_bf16 v[62:65], v[162:165], v[246:249], v[174:177]
	s_setprio 0
	s_branch .LBB0_970

; #define LAS __attribute__((address_space(3)))
; __device__ __forceinline__ float ex2(float x) { return __builtin_amdgcn_exp2f(x); }
; __device__ __forceinline__ f32x4 mfma16(bf16x8 a, bf16x8 b, f32x4 c) { return __builtin_amdgcn_mfma_f32_16x16x32_bf16(a, b, c, 0, 0, 0); }
;   __device__ __forceinline__ bf16_t* W() const { return (bf16_t*)(ws + WS_W); }
; template <int NT, int NKK, int NDT, int MODE, bool MASK> ...
;     ...
;   f32x4 s[NT][4];
;   __builtin_amdgcn_s_setprio(1);
; #pragma unroll
;   for (int t = 0; t < 4; ++t)
; #pragma unroll
;     for (int kk = 0; kk < NKK; ++kk) {
;       const bf16x8 kf = *(LAS const bf16x8*)(Kl + (16 * t + r) * KSTR + (32 * kk + 8 * lg) * 2);
; #pragma unroll
;       for (int j = 0; j < NT; ++j) s[j][t] = mfma16(kf, qf[j][kk], kk == 0 ? (f32x4){0.f, 0.f, 0.f, 0.f} : s[j][t]);
;     }
;   __builtin_amdgcn_s_setprio(0);
;   bf16x8 pf[NT][2];
; #pragma unroll
;   for (int j = 0; j < NT; ++j) {
;     float mx = -INFINITY;
; #pragma unroll
;     for (int t = 0; t < 4; ++t)
; #pragma unroll
;       for (int i = 0; i < 4; ++i) {
;         if (MASK) { const int kp = kpos0 + 16 * t + 4 * lg + i; if (!mask_ok<MODE>(tq[j], kp, W)) s[j][t][i] = -INFINITY; }
;         mx = fmaxf(mx, s[j][t][i]);
;       }
;     mx = max_x16_x32(mx);
;     if (__any(mx > m[j] + 8.0f / c)) {
;       const float mnew = fmaxf(m[j], mx);
;       const float ms2 = (mnew == -INFINITY) ? 0.f : mnew;
;       const float alpha = ex2((m[j] - ms2) * c);
;       m[j] = mnew; l[j] *= alpha;
; #pragma unroll
;       for (int dt = 0; dt < NDT; ++dt) o[j][dt] *= alpha;
;     }
;     const float mc = ((m[j] == -INFINITY) ? 0.f : m[j]) * c;
.LBB0_983:
	s_waitcnt lgkmcnt(0)
	s_barrier
	s_add_i32 s8, s43, 0xffffff81
	s_cmp_gt_i32 s8, s40
	s_cbranch_scc1 .LBB0_1010
	s_sub_i32 s8, s43, 64
	s_cmp_gt_i32 s8, s25
	s_setprio 1
	v_add_u32_e32 v1, s59, v236
	s_waitcnt lgkmcnt(0)
	v_add_u32_e32 v94, v1, v237
	ds_read_b128 v[134:137], v94
	ds_read_b128 v[130:133], v94 offset:64
	ds_read_b128 v[126:129], v94 offset:128
	ds_read_b128 v[122:125], v94 offset:3328
	ds_read_b128 v[118:121], v94 offset:3392
	ds_read_b128 v[114:117], v94 offset:3456
	ds_read_b128 v[106:109], v94 offset:6656
	ds_read_b128 v[98:101], v94 offset:6720
	v_add_u32_e32 v201, v1, v238
	ds_read_b128 v[110:113], v94 offset:6784
	ds_read_b128 v[102:105], v201
	ds_read_b128 v[94:97], v201 offset:64
	s_mov_b64 s[20:21], -1
	v_add_f32_e32 v1, 0x4259535f, v220
	s_cbranch_scc1 .LBB0_1001
	s_waitcnt lgkmcnt(10)
	v_mfma_f32_16x16x32_bf16 v[138:141], v[134:137], v[18:21], 0
	ds_read_b128 v[146:149], v201 offset:128
	v_mov_b32_e32 v234, 0x260
	v_mfma_f32_16x16x32_bf16 v[142:145], v[134:137], v[10:13], 0
	s_waitcnt lgkmcnt(10)
	v_mfma_f32_16x16x32_bf16 v[138:141], v[130:133], v[2:5], v[138:141]
	v_mov_b64_e32 v[222:223], v[220:221]
	v_mfma_f32_16x16x32_bf16 v[142:145], v[130:133], v[14:17], v[142:145]
	v_mov_b64_e32 v[224:225], v[218:219]
	s_waitcnt lgkmcnt(9)
	v_mfma_f32_16x16x32_bf16 v[182:185], v[126:129], v[6:9], v[138:141]
	v_mfma_f32_16x16x32_bf16 v[166:169], v[126:129], v[22:25], v[142:145]
	v_mov_b32_e32 v187, v220
	s_waitcnt lgkmcnt(8)
	v_mfma_f32_16x16x32_bf16 v[138:141], v[122:125], v[18:21], 0
	v_add_f32_e32 v158, 0x4259535f, v221
	v_mfma_f32_16x16x32_bf16 v[142:145], v[122:125], v[10:13], 0
	v_mul_f32_e32 v159, 0x3e16c740, v220
	s_waitcnt lgkmcnt(7)
	v_mfma_f32_16x16x32_bf16 v[138:141], v[118:121], v[2:5], v[138:141]
	v_cmp_neq_f32_e64 s[22:23], s81, v220
	v_mfma_f32_16x16x32_bf16 v[142:145], v[118:121], v[14:17], v[142:145]
	s_waitcnt lgkmcnt(6)
	v_mfma_f32_16x16x32_bf16 v[178:181], v[114:117], v[6:9], v[138:141]
	v_mfma_f32_16x16x32_bf16 v[154:157], v[114:117], v[22:25], v[142:145]
	v_cndmask_b32_e64 v159, 0, v159, s[22:23]
	s_waitcnt lgkmcnt(5)
	v_mfma_f32_16x16x32_bf16 v[138:141], v[106:109], v[18:21], 0
	v_mul_f32_e32 v160, 0x3e16c740, v221
	v_mfma_f32_16x16x32_bf16 v[142:145], v[106:109], v[10:13], 0
	v_cmp_neq_f32_e64 s[22:23], s81, v221
	v_max3_f32 v188, v182, s81, v183
	s_waitcnt lgkmcnt(4)
	v_mfma_f32_16x16x32_bf16 v[138:141], v[98:101], v[2:5], v[138:141]
	v_max3_f32 v188, v188, v184, v185
	v_mfma_f32_16x16x32_bf16 v[142:145], v[98:101], v[14:17], v[142:145]
	v_max3_f32 v189, v166, s81, v167
	s_waitcnt lgkmcnt(3)
	v_mfma_f32_16x16x32_bf16 v[174:177], v[110:113], v[6:9], v[138:141]
	v_cndmask_b32_e64 v160, 0, v160, s[22:23]
	v_max3_f32 v189, v189, v168, v169
	v_mfma_f32_16x16x32_bf16 v[150:153], v[110:113], v[22:25], v[142:145]
	s_waitcnt lgkmcnt(2)
	v_mfma_f32_16x16x32_bf16 v[138:141], v[102:105], v[18:21], 0
	v_mfma_f32_16x16x32_bf16 v[142:145], v[102:105], v[10:13], 0
	v_max3_f32 v188, v188, v178, v179
	s_waitcnt lgkmcnt(1)
	v_mfma_f32_16x16x32_bf16 v[138:141], v[94:97], v[2:5], v[138:141]
	v_max3_f32 v188, v188, v180, v181
	v_mfma_f32_16x16x32_bf16 v[142:145], v[94:97], v[14:17], v[142:145]
	v_max3_f32 v189, v189, v154, v155
	s_waitcnt lgkmcnt(0)
	v_mfma_f32_16x16x32_bf16 v[170:173], v[146:149], v[6:9], v[138:141]
	v_max3_f32 v189, v189, v156, v157
	v_mfma_f32_16x16x32_bf16 v[142:145], v[146:149], v[22:25], v[142:145]
	s_setprio 0
	s_nop 3
	v_max3_f32 v138, v188, v174, v175
	v_max3_f32 v138, v138, v176, v177
	v_max3_f32 v138, v138, v170, v171
	v_max3_f32 v138, v138, v172, v173
	v_mov_b32_e32 v139, v138
	s_nop 1
	v_permlane16_swap_b32_e32 v138, v139
	v_max_f32_e32 v138, v138, v139
	v_mov_b32_e32 v139, v138
	s_nop 1
	v_permlane32_swap_b32_e32 v138, v139
	v_max_f32_e32 v186, v138, v139
	v_cmp_gt_f32_e32 vcc, v186, v1
	s_cbranch_vccz .LBB0_987
	v_max_f32_e32 v138, v186, v186
	v_max_f32_e32 v139, v220, v220
	v_max_f32_e32 v222, v139, v138
	v_cmp_neq_f32_e32 vcc, s81, v222
	v_mov_b32_e32 v223, v221
	v_mov_b32_e32 v225, v219
	v_cndmask_b32_e32 v138, 0, v222, vcc
	v_sub_f32_e32 v138, v220, v138
	v_mul_f32_e32 v138, 0x3e16c740, v138
	v_exp_f32_e32 v138, v138
	v_mov_b32_e32 v187, v222
	v_mul_f32_e32 v224, v218, v138
	v_pk_mul_f32 v[92:93], v[92:93], v[138:139] op_sel_hi:[1,0]
	v_pk_mul_f32 v[90:91], v[90:91], v[138:139] op_sel_hi:[1,0]
	v_pk_mul_f32 v[88:89], v[88:89], v[138:139] op_sel_hi:[1,0]
	v_pk_mul_f32 v[86:87], v[86:87], v[138:139] op_sel_hi:[1,0]
	v_pk_mul_f32 v[76:77], v[76:77], v[138:139] op_sel_hi:[1,0]
	v_pk_mul_f32 v[74:75], v[74:75], v[138:139] op_sel_hi:[1,0]
	v_pk_mul_f32 v[68:69], v[68:69], v[138:139] op_sel_hi:[1,0]
	v_pk_mul_f32 v[66:67], v[66:67], v[138:139] op_sel_hi:[1,0]
	v_mul_f32_e32 v159, 0x3e16c740, v187
	v_cmp_neq_f32_e32 vcc, s81, v187
	s_nop 1
	v_cndmask_b32_e32 v159, 0, v159, vcc

; __device__ __forceinline__ float ex2(float x) { return __builtin_amdgcn_exp2f(x); }
; __device__ __forceinline__ f32x4 mfma16(bf16x8 a, bf16x8 b, f32x4 c) { return __builtin_amdgcn_mfma_f32_16x16x32_bf16(a, b, c, 0, 0, 0); }
; __device__ __forceinline__ s16x4 ds_tr(LAS const unsigned char* p) { return __builtin_bit_cast(s16x4, __builtin_amdgcn_ds_read_tr16_b64_v4i16((LAS v4i16_t*)p)); }
; template <int NT, int NKK, int NDT, int MODE, bool MASK> ...
;     ...
;     const float mc = ((m[j] == -INFINITY) ? 0.f : m[j]) * c;
;     float p[4][4], ps = 0.f;
; #pragma unroll
;     for (int t = 0; t < 4; ++t)
; #pragma unroll
;       for (int i = 0; i < 4; ++i) { p[t][i] = ex2(s[j][t][i] * c - mc); ps += p[t][i]; }
;     l[j] += ps;
;     pf[j][0] = pack8(p[0], p[1]); pf[j][1] = pack8(p[2], p[3]);
;   }
;   __builtin_amdgcn_s_setprio(1);
; #pragma unroll
;   for (int st = 0; st < 2; ++st)
; #pragma unroll
;     for (int dt = 0; dt < NDT; ++dt) {
;       const s16x4 v0 = ds_tr(Vl + (32 * st + 4 * lg + vq) * VSTR + (16 * dt + 4 * vp) * 2);
;       const s16x4 v1 = ds_tr(Vl + (32 * st + 16 + 4 * lg + vq) * VSTR + (16 * dt + 4 * vp) * 2);
;       const bf16x8 vf = (bf16x8){v0[0], v0[1], v0[2], v0[3], v1[0], v1[1], v1[2], v1[3]};
; #pragma unroll
;       for (int j = 0; j < NT; ++j) o[j][dt] = mfma16(vf, pf[j][st], o[j][dt]);
;     }
.LBB0_999:
.LBB0_1000:
	v_cvt_pk_bf16_f32 v173, v196, v173
	v_cvt_pk_bf16_f32 v172, v232, v228
	v_cvt_pk_bf16_f32 v228, v205, v207
	v_fma_f32 v166, v166, s88, -v160
	v_exp_f32_e32 v166, v166
	v_fma_f32 v167, v167, s88, -v160
	v_exp_f32_e32 v167, v167
	v_fma_f32 v168, v168, s88, -v160
	v_exp_f32_e32 v168, v168
	v_fma_f32 v169, v169, s88, -v160
	v_exp_f32_e32 v169, v169
	v_fma_f32 v154, v154, s88, -v160
	v_exp_f32_e32 v154, v154
	v_fma_f32 v155, v155, s88, -v160
	v_add_f32_e32 v197, v167, v166
	v_exp_f32_e32 v155, v155
	v_fma_f32 v156, v156, s88, -v160
	v_add_f32_e32 v197, v168, v197
	v_exp_f32_e32 v156, v156
	v_fma_f32 v157, v157, s88, -v160
	v_add_f32_e32 v197, v169, v197
	v_exp_f32_e32 v157, v157
	v_fma_f32 v150, v150, s88, -v160
	v_add_f32_e32 v197, v154, v197
	v_exp_f32_e32 v150, v150
	v_fma_f32 v151, v151, s88, -v160
	v_add_f32_e32 v197, v155, v197
	v_exp_f32_e32 v151, v151
	v_fma_f32 v152, v152, s88, -v160
	v_add_f32_e32 v197, v156, v197
	v_exp_f32_e32 v152, v152
	v_fma_f32 v153, v153, s88, -v160
	v_add_f32_e32 v197, v157, v197
	v_exp_f32_e32 v153, v153
	v_fma_f32 v142, v142, s88, -v160
	v_add_f32_e32 v197, v150, v197
	v_exp_f32_e32 v198, v142
	v_fma_f32 v142, v143, s88, -v160
	v_add_f32_e32 v197, v151, v197
	v_exp_f32_e32 v199, v142
	v_fma_f32 v142, v144, s88, -v160
	v_add_f32_e32 v197, v152, v197
	v_exp_f32_e32 v205, v142
	v_fma_f32 v142, v145, s88, -v160
	v_add_f32_e32 v197, v153, v197
	v_exp_f32_e32 v196, v142
	v_add_f32_e32 v142, v198, v197
	v_add_f32_e32 v142, v199, v142
	v_add_f32_e32 v142, v205, v142
	v_add_f32_e32 v142, v196, v142
	v_add_f32_e32 v225, v225, v142
	v_cvt_pk_bf16_f32 v142, v166, v167
	v_cvt_pk_bf16_f32 v143, v168, v169
	v_cvt_pk_bf16_f32 v144, v154, v155
	v_cvt_pk_bf16_f32 v145, v156, v157
	v_cvt_pk_bf16_f32 v170, v252, v231
	v_cvt_pk_bf16_f32 v171, v229, v230
	v_cvt_pk_bf16_f32 v229, v246, v247
	v_cvt_pk_bf16_f32 v230, v248, v249
	v_cvt_pk_bf16_f32 v231, v250, v251
	v_cvt_pk_bf16_f32 v246, v150, v151
	v_cvt_pk_bf16_f32 v247, v152, v153
	v_cvt_pk_bf16_f32 v248, v198, v199
	v_cvt_pk_bf16_f32 v249, v205, v196
	s_setprio 1
	v_add3_u32 v196, s59, v240, v239
	ds_read_b64_tr_b16 v[152:153], v196 offset:15872
	ds_read_b64_tr_b16 v[150:151], v196 offset:13312
	ds_read_b64_tr_b16 v[154:155], v196 offset:13344
	ds_read_b64_tr_b16 v[156:157], v196 offset:15904
	ds_read_b64_tr_b16 v[166:167], v196 offset:13376
	ds_read_b64_tr_b16 v[168:169], v196 offset:15936
	s_mov_b64 s[20:21], 0
	s_waitcnt lgkmcnt(4)
	v_mfma_f32_16x16x32_bf16 v[158:161], v[150:153], v[228:231], v[90:93]
	v_mfma_f32_16x16x32_bf16 v[150:153], v[150:153], v[142:145], v[82:85]
	v_mov_b64_e32 v[218:219], v[224:225]
	s_waitcnt lgkmcnt(0)
	v_mfma_f32_16x16x32_bf16 v[182:185], v[166:169], v[228:231], v[74:77]
	s_nop 2
	ds_read_b64_tr_b16 v[146:147], v196 offset:13408
	ds_read_b64_tr_b16 v[148:149], v196 offset:15968
	v_mfma_f32_16x16x32_bf16 v[162:165], v[154:157], v[228:231], v[86:89]
	v_mov_b64_e32 v[220:221], v[222:223]
	v_mfma_f32_16x16x32_bf16 v[154:157], v[154:157], v[142:145], v[78:81]
	v_mfma_f32_16x16x32_bf16 v[166:169], v[166:169], v[142:145], v[70:73]
	s_waitcnt lgkmcnt(0)
	v_mfma_f32_16x16x32_bf16 v[174:177], v[146:149], v[142:145], v[62:65]
	ds_read_b64_tr_b16 v[142:143], v196 offset:18432
	ds_read_b64_tr_b16 v[144:145], v196 offset:20992
	v_mfma_f32_16x16x32_bf16 v[178:181], v[146:149], v[228:231], v[66:69]
	s_waitcnt lgkmcnt(0)
	v_mfma_f32_16x16x32_bf16 v[90:93], v[142:145], v[170:173], v[158:161]
	v_mfma_f32_16x16x32_bf16 v[82:85], v[142:145], v[246:249], v[150:153]
	s_nop 2
	ds_read_b64_tr_b16 v[150:151], v196 offset:18464
	ds_read_b64_tr_b16 v[152:153], v196 offset:21024
	ds_read_b64_tr_b16 v[158:159], v196 offset:18496
	ds_read_b64_tr_b16 v[160:161], v196 offset:21056
	s_waitcnt lgkmcnt(2)
	v_mfma_f32_16x16x32_bf16 v[86:89], v[150:153], v[170:173], v[162:165]
	s_nop 2
	ds_read_b64_tr_b16 v[162:163], v196 offset:18528
	ds_read_b64_tr_b16 v[164:165], v196 offset:21088
	v_mfma_f32_16x16x32_bf16 v[78:81], v[150:153], v[246:249], v[154:157]
	s_waitcnt lgkmcnt(2)
	v_mfma_f32_16x16x32_bf16 v[74:77], v[158:161], v[170:173], v[182:185]
	v_mfma_f32_16x16x32_bf16 v[70:73], v[158:161], v[246:249], v[166:169]
	s_waitcnt lgkmcnt(0)
	v_mfma_f32_16x16x32_bf16 v[66:69], v[162:165], v[170:173], v[178:181]
	v_mfma_f32_16x16x32_bf16 v[62:65], v[162:165], v[246:249], v[174:177]
	s_setprio 0
	s_branch .LBB0_1010

; #define LAS __attribute__((address_space(3)))
; __device__ __forceinline__ float ex2(float x) { return __builtin_amdgcn_exp2f(x); }
; __device__ __forceinline__ f32x4 mfma16(bf16x8 a, bf16x8 b, f32x4 c) { return __builtin_amdgcn_mfma_f32_16x16x32_bf16(a, b, c, 0, 0, 0); }
;   __device__ __forceinline__ bf16_t* W() const { return (bf16_t*)(ws + WS_W); }
; template <int NT, int NKK, int NDT, int MODE, bool MASK> ...
;     ...
;   f32x4 s[NT][4];
;   __builtin_amdgcn_s_setprio(1);
; #pragma unroll
;   for (int t = 0; t < 4; ++t)
; #pragma unroll
;     for (int kk = 0; kk < NKK; ++kk) {
;       const bf16x8 kf = *(LAS const bf16x8*)(Kl + (16 * t + r) * KSTR + (32 * kk + 8 * lg) * 2);
; #pragma unroll
;       for (int j = 0; j < NT; ++j) s[j][t] = mfma16(kf, qf[j][kk], kk == 0 ? (f32x4){0.f, 0.f, 0.f, 0.f} : s[j][t]);
;     }
;   __builtin_amdgcn_s_setprio(0);
;   bf16x8 pf[NT][2];
; #pragma unroll
;   for (int j = 0; j < NT; ++j) {
;     float mx = -INFINITY;
; #pragma unroll
;     for (int t = 0; t < 4; ++t)
; #pragma unroll
;       for (int i = 0; i < 4; ++i) {
;         if (MASK) { const int kp = kpos0 + 16 * t + 4 * lg + i; if (!mask_ok<MODE>(tq[j], kp, W)) s[j][t][i] = -INFINITY; }
;         mx = fmaxf(mx, s[j][t][i]);
;       }
;     mx = max_x16_x32(mx);
;     if (__any(mx > m[j] + 8.0f / c)) {
;       const float mnew = fmaxf(m[j], mx);
;       const float ms2 = (mnew == -INFINITY) ? 0.f : mnew;
;       const float alpha = ex2((m[j] - ms2) * c);
;       m[j] = mnew; l[j] *= alpha;
; #pragma unroll
;       for (int dt = 0; dt < NDT; ++dt) o[j][dt] *= alpha;
;     }
;     const float mc = ((m[j] == -INFINITY) ? 0.f : m[j]) * c;
.LBB0_1023:
	s_waitcnt lgkmcnt(0)
	s_barrier
	s_sub_i32 s8, s43, 63
	s_cmp_gt_i32 s8, s40
	s_cbranch_scc1 .LBB0_1050
	s_cmp_gt_i32 s43, s25
	s_setprio 1
	v_add_u32_e32 v1, s45, v236
	s_waitcnt lgkmcnt(0)
	v_add_u32_e32 v94, v1, v237
	ds_read_b128 v[134:137], v94
	ds_read_b128 v[130:133], v94 offset:64
	ds_read_b128 v[126:129], v94 offset:128
	ds_read_b128 v[122:125], v94 offset:3328
	ds_read_b128 v[118:121], v94 offset:3392
	ds_read_b128 v[114:117], v94 offset:3456
	ds_read_b128 v[106:109], v94 offset:6656
	ds_read_b128 v[98:101], v94 offset:6720
	v_add_u32_e32 v201, v1, v238
	ds_read_b128 v[110:113], v94 offset:6784
	ds_read_b128 v[102:105], v201
	ds_read_b128 v[94:97], v201 offset:64
	s_mov_b64 s[20:21], -1
	v_add_f32_e32 v1, 0x4259535f, v220
	s_cbranch_scc1 .LBB0_1041
	s_waitcnt lgkmcnt(10)
	v_mfma_f32_16x16x32_bf16 v[138:141], v[134:137], v[18:21], 0
	ds_read_b128 v[146:149], v201 offset:128
	v_mov_b32_e32 v234, 0x260
	v_mfma_f32_16x16x32_bf16 v[142:145], v[134:137], v[10:13], 0
	s_waitcnt lgkmcnt(10)
	v_mfma_f32_16x16x32_bf16 v[138:141], v[130:133], v[2:5], v[138:141]
	v_mov_b64_e32 v[222:223], v[220:221]
	v_mfma_f32_16x16x32_bf16 v[142:145], v[130:133], v[14:17], v[142:145]
	v_mov_b64_e32 v[224:225], v[218:219]
	s_waitcnt lgkmcnt(9)
	v_mfma_f32_16x16x32_bf16 v[182:185], v[126:129], v[6:9], v[138:141]
	v_mfma_f32_16x16x32_bf16 v[166:169], v[126:129], v[22:25], v[142:145]
	v_mov_b32_e32 v187, v220
	s_waitcnt lgkmcnt(8)
	v_mfma_f32_16x16x32_bf16 v[138:141], v[122:125], v[18:21], 0
	v_add_f32_e32 v158, 0x4259535f, v221
	v_mfma_f32_16x16x32_bf16 v[142:145], v[122:125], v[10:13], 0
	v_mul_f32_e32 v159, 0x3e16c740, v220
	s_waitcnt lgkmcnt(7)
	v_mfma_f32_16x16x32_bf16 v[138:141], v[118:121], v[2:5], v[138:141]
	v_cmp_neq_f32_e64 s[22:23], s81, v220
	v_mfma_f32_16x16x32_bf16 v[142:145], v[118:121], v[14:17], v[142:145]
	s_waitcnt lgkmcnt(6)
	v_mfma_f32_16x16x32_bf16 v[178:181], v[114:117], v[6:9], v[138:141]
	v_mfma_f32_16x16x32_bf16 v[154:157], v[114:117], v[22:25], v[142:145]
	v_cndmask_b32_e64 v159, 0, v159, s[22:23]
	s_waitcnt lgkmcnt(5)
	v_mfma_f32_16x16x32_bf16 v[138:141], v[106:109], v[18:21], 0
	v_mul_f32_e32 v160, 0x3e16c740, v221
	v_mfma_f32_16x16x32_bf16 v[142:145], v[106:109], v[10:13], 0
	v_cmp_neq_f32_e64 s[22:23], s81, v221
	v_max3_f32 v188, v182, s81, v183
	s_waitcnt lgkmcnt(4)
	v_mfma_f32_16x16x32_bf16 v[138:141], v[98:101], v[2:5], v[138:141]
	v_max3_f32 v188, v188, v184, v185
	v_mfma_f32_16x16x32_bf16 v[142:145], v[98:101], v[14:17], v[142:145]
	v_max3_f32 v189, v166, s81, v167
	s_waitcnt lgkmcnt(3)
	v_mfma_f32_16x16x32_bf16 v[174:177], v[110:113], v[6:9], v[138:141]
	v_cndmask_b32_e64 v160, 0, v160, s[22:23]
	v_max3_f32 v189, v189, v168, v169
	v_mfma_f32_16x16x32_bf16 v[150:153], v[110:113], v[22:25], v[142:145]
	s_waitcnt lgkmcnt(2)
	v_mfma_f32_16x16x32_bf16 v[138:141], v[102:105], v[18:21], 0
	v_mfma_f32_16x16x32_bf16 v[142:145], v[102:105], v[10:13], 0
	v_max3_f32 v188, v188, v178, v179
	s_waitcnt lgkmcnt(1)
	v_mfma_f32_16x16x32_bf16 v[138:141], v[94:97], v[2:5], v[138:141]
	v_max3_f32 v188, v188, v180, v181
	v_mfma_f32_16x16x32_bf16 v[142:145], v[94:97], v[14:17], v[142:145]
	v_max3_f32 v189, v189, v154, v155
	s_waitcnt lgkmcnt(0)
	v_mfma_f32_16x16x32_bf16 v[170:173], v[146:149], v[6:9], v[138:141]
	v_max3_f32 v189, v189, v156, v157
	v_mfma_f32_16x16x32_bf16 v[142:145], v[146:149], v[22:25], v[142:145]
	s_setprio 0
	s_nop 3
	v_max3_f32 v138, v188, v174, v175
	v_max3_f32 v138, v138, v176, v177
	v_max3_f32 v138, v138, v170, v171
	v_max3_f32 v138, v138, v172, v173
	v_mov_b32_e32 v139, v138
	s_nop 1
	v_permlane16_swap_b32_e32 v138, v139
	v_max_f32_e32 v138, v138, v139
	v_mov_b32_e32 v139, v138
	s_nop 1
	v_permlane32_swap_b32_e32 v138, v139
	v_max_f32_e32 v186, v138, v139
	v_cmp_gt_f32_e32 vcc, v186, v1
	s_cbranch_vccz .LBB0_1027
	v_max_f32_e32 v138, v186, v186
	v_max_f32_e32 v139, v220, v220
	v_max_f32_e32 v222, v139, v138
	v_cmp_neq_f32_e32 vcc, s81, v222
	v_mov_b32_e32 v223, v221
	v_mov_b32_e32 v225, v219
	v_cndmask_b32_e32 v138, 0, v222, vcc
	v_sub_f32_e32 v138, v220, v138
	v_mul_f32_e32 v138, 0x3e16c740, v138
	v_exp_f32_e32 v138, v138
	v_mov_b32_e32 v187, v222
	v_mul_f32_e32 v224, v218, v138
	v_pk_mul_f32 v[92:93], v[92:93], v[138:139] op_sel_hi:[1,0]
	v_pk_mul_f32 v[90:91], v[90:91], v[138:139] op_sel_hi:[1,0]
	v_pk_mul_f32 v[88:89], v[88:89], v[138:139] op_sel_hi:[1,0]
	v_pk_mul_f32 v[86:87], v[86:87], v[138:139] op_sel_hi:[1,0]
	v_pk_mul_f32 v[76:77], v[76:77], v[138:139] op_sel_hi:[1,0]
	v_pk_mul_f32 v[74:75], v[74:75], v[138:139] op_sel_hi:[1,0]
	v_pk_mul_f32 v[68:69], v[68:69], v[138:139] op_sel_hi:[1,0]
	v_pk_mul_f32 v[66:67], v[66:67], v[138:139] op_sel_hi:[1,0]
	v_mul_f32_e32 v159, 0x3e16c740, v187
	v_cmp_neq_f32_e32 vcc, s81, v187
	s_nop 1
	v_cndmask_b32_e32 v159, 0, v159, vcc
